# diff attention: K tiles DMA'd four tiles ahead (slot refilled one step earlier) and in-loop DMA wait relaxed to vmcnt(8): 2.5 steps of latency slack instead of 1.5
# speedup vs baseline: 1.0031x; 1.0031x over previous
; #define EX(v) __builtin_amdgcn_exp2f(v)
; __device__ __forceinline__ void attn_unit_d16(const UnitDesc& U, char* shm, float lam, const float* subw) {
;     ...
;     const int tid = threadIdx.x, lane = tid & 63, c16 = lane & 15, g = lane >> 4; const int wid = __builtin_amdgcn_readfirstlane(tid >> 6);
;     const unsigned lds0 = (unsigned)(uintptr_t)shm;
;     const int map = wid >> 2;
;     unsigned koff, voff; unsigned kdst[NPK], vdst[NPV];
;     { const int key = 8 * wid + (lane >> 3), pp = lane & 7;
;       koff = (unsigned)(key * U.KP + (pp ^ ((key >> 1) & 7)) * 8) * 2u; voff = (unsigned)(key * U.VP + ((((pp >> 1) ^ ((key >> 1) & 3)) << 1) + (pp & 1)) * 8) * 2u;
; #pragma unroll
;       for (int pc = 0; pc < NPK; ++pc) kdst[pc] = lds0 + LDS_K + pc * 8192 + wid * 1024;
; #pragma unroll
;       for (int pc = 0; pc < NPV; ++pc) vdst[pc] = lds0 + LDS_V + pc * 8192 + wid * 1024; }
;     ...
;     const lds_cptr shm3 = (lds_cptr)shm;
;     lds_cptr kpb[2];
; #pragma unroll
;     for (int ds = 0; ds < 2; ++ds) kpb[ds] = shm3 + LDS_K + map * 8192 + c16 * 128 + (((4 * ds + g) ^ (c16 >> 1)) << 4);
;     lds_cptr vpb[4];
;     { const int q4 = c16 >> 2, p = c16 & 3, ko = 4 * g + q4, swz = (ko >> 1) & 3;
; #pragma unroll
;       for (int b = 0; b < 4; ++b) vpb[b] = shm3 + LDS_V + ko * 128 + ((b ^ swz) << 5) + p * 8; }
;     bf16x8 qr[2][2];
; #pragma unroll
;     for (int qt = 0; qt < 2; ++qt)
; #pragma unroll
;         for (int ds = 0; ds < 2; ++ds) qr[qt][ds] = *reinterpret_cast<const bf16x8*>(U.Qw + (size_t)(16 * qt + c16) * 512 + 32 * ds + 8 * g);
;     ...
;     DMA_K(0, 0); DMA_V(0, 0); DMA_K(1, 1); DMA_K(2, 2); DMA_V(1, 1);
;     ATT_WAIT_BAR(8);
;     { const int kn_ = 0;
; #pragma unroll
;       for (int j = 0; j < 8; ++j) KRD16(j); }
; #pragma unroll
;     for (int kt = 0; kt < 4; ++kt)
; #pragma unroll
;         for (int qt = 0; qt < 2; ++qt) { S[kt][qt] = MF16(kf[kt][0], qr[qt][0], zero4); S[kt][qt] = MF16(kf[kt][1], qr[qt][1], S[kt][qt]); }
; #pragma unroll
;     for (int kt = 0; kt < 4; ++kt)
; #pragma unroll
;         for (int qt = 0; qt < 2; ++qt)
; #pragma unroll
;             for (int r = 0; r < 4; ++r) S[kt][qt][r] = EX(S[kt][qt][r]);
; #pragma unroll
;     for (int qt = 0; qt < 2; ++qt)
; #pragma unroll
;         for (int ks = 0; ks < 2; ++ks) { pa[qt][ks][0] = cvtpk_s(S[2 * ks][qt][0], S[2 * ks][qt][1]); pa[qt][ks][1] = cvtpk_s(S[2 * ks][qt][2], S[2 * ks][qt][3]);
.LBB0_443:
	s_mul_i32 s53, s53, 3
	s_ashr_i32 s68, s52, 1
	s_lshl_b32 s0, s12, 5
	s_add_i32 s8, s68, s53
	s_and_b32 s0, s0, 32
	s_ashr_i32 s10, s8, 2
	s_or_b32 s12, s0, s13
	s_ashr_i32 s11, s10, 31
	s_lshl_b32 s12, s12, 7
	s_lshl_b64 s[0:1], s[10:11], 13
	s_or_b32 s12, s12, s43
	s_or_b32 s0, s0, s12
	s_lshl_b64 s[12:13], s[0:1], 10
	s_add_u32 s12, s20, s12
	s_addc_u32 s13, s21, s13
	s_lshl_b32 s8, s8, 7
	s_and_b32 s8, s8, 0x180
	s_lshl_b32 s30, s8, 1
	s_add_u32 s12, s12, s30
	s_addc_u32 s13, s13, 0
	s_add_u32 s12, s12, s48
	s_addc_u32 s13, s13, 0
	v_mov_b32_e32 v187, v183
	v_lshl_add_u64 v[2:3], s[12:13], 0, v[186:187]
	v_mov_b32_e32 v189, v183
	v_lshl_add_u64 v[2:3], v[2:3], 0, v[188:189]
	global_load_dwordx4 v[10:13], v[2:3], off
	global_load_dwordx4 v[14:17], v[2:3], off offset:64
	v_add_co_u32_e32 v2, vcc, s45, v2
	s_lshl_b64 s[14:15], s[10:11], 23
	s_nop 0
	v_addc_co_u32_e32 v3, vcc, 0, v3, vcc
	global_load_dwordx4 v[18:21], v[2:3], off
	global_load_dwordx4 v[22:25], v[2:3], off offset:64
	s_add_u32 s10, s22, s14
	s_addc_u32 s11, s23, s15
	s_add_u32 s28, s10, s30
	s_addc_u32 s29, s11, 0
	s_add_u32 s10, s24, s14
	s_addc_u32 s11, s25, s15
	s_add_u32 s10, s10, s30
	v_readfirstlane_b32 s12, v180
	s_addc_u32 s11, s11, 0
	s_lshr_b32 s13, s12, 6
	v_lshl_or_b32 v1, s13, 3, v191
	s_lshl_b32 s30, s13, 10
	v_lshlrev_b32_e32 v2, 10, v1
	v_lshrrev_b32_e32 v1, 1, v1
	s_cmp_lg_u32 0, -1
	v_xor_b32_e32 v1, v1, v180
	s_cselect_b32 s31, 0, 0
	s_lshl_b32 s40, s12, 5
	v_lshlrev_b32_e32 v1, 4, v1
	s_add_i32 s30, s30, s31
	s_and_b32 s40, s40, 0x7fffe000
	s_waitcnt vmcnt(0)
	v_and_or_b32 v157, v1, s47, v2
	s_add_i32 s31, s30, 0x2000
	s_add_i32 s38, s30, 0x10000
	s_add_i32 s39, s30, 0x12000
	v_add_u32_e32 v6, s40, v194
	s_mov_b32 s40, m0
	s_mov_b32 m0, s30
	s_nop 0
	global_load_lds_dwordx4 v157, s[28:29]
	s_mov_b32 m0, s40
	s_add_u32 s40, s28, 0x80
	s_addc_u32 s41, s29, 0
	s_mov_b32 s52, m0
	s_mov_b32 m0, s31
	s_nop 0
	global_load_lds_dwordx4 v157, s[40:41]
	s_mov_b32 m0, s52
	v_or_b32_e32 v156, v2, v192
	s_mov_b32 s40, m0
	s_mov_b32 m0, s38
	s_nop 0
	global_load_lds_dwordx4 v156, s[10:11]
	s_mov_b32 m0, s40
	s_add_u32 s40, s10, 0x80
	s_addc_u32 s41, s11, 0
	s_mov_b32 s52, m0
	s_mov_b32 m0, s39
	s_nop 0
	global_load_lds_dwordx4 v156, s[40:41]
	s_mov_b32 m0, s52
	s_add_u32 s52, s28, 0x10000
	s_addc_u32 s53, s29, 0
	s_add_i32 s40, s30, 0x4000
	s_mov_b32 s41, m0
	s_mov_b32 m0, s40
	s_nop 0
	global_load_lds_dwordx4 v157, s[52:53]
	s_mov_b32 m0, s41
	s_add_u32 s52, s28, 0x10080
	s_addc_u32 s53, s29, 0
	s_add_i32 s41, s31, 0x4000
	s_mov_b32 s62, m0
	s_mov_b32 m0, s41
	s_nop 0
	global_load_lds_dwordx4 v157, s[52:53]
	s_mov_b32 m0, s62
	s_add_u32 s62, s28, 0x20000
	s_addc_u32 s63, s29, 0
	s_add_i32 s52, s30, 0x8000
	s_mov_b32 s53, m0
	s_mov_b32 m0, s52
	s_nop 0
	global_load_lds_dwordx4 v157, s[62:63]
	s_mov_b32 m0, s53
	s_add_u32 s62, s28, 0x20080
	s_addc_u32 s63, s29, 0
	s_add_i32 s53, s31, 0x8000
	s_mov_b32 s66, m0
	s_mov_b32 m0, s53
	s_nop 0
	global_load_lds_dwordx4 v157, s[62:63]
	s_mov_b32 m0, s66
	s_add_u32 s66, s10, 0x10000
	s_addc_u32 s67, s11, 0
	s_add_i32 s62, s38, 0x4000
	s_mov_b32 s63, m0
	s_mov_b32 m0, s62
	s_nop 0
	global_load_lds_dwordx4 v156, s[66:67]
	s_mov_b32 m0, s63
	s_add_u32 s66, s10, 0x10080
	s_addc_u32 s67, s11, 0
	s_add_i32 s63, s39, 0x4000
	s_mov_b32 s69, m0
	s_mov_b32 m0, s63
	s_nop 0
	global_load_lds_dwordx4 v156, s[66:67]
	s_mov_b32 m0, s69
	v_add_u32_e32 v1, v6, v195
	s_waitcnt vmcnt(8) lgkmcnt(0)
	s_barrier
	ds_read_b128 v[2:5], v1
	v_add_u32_e32 v115, v6, v196
	ds_read_b128 v[6:9], v1 offset:2048
	s_waitcnt lgkmcnt(1)
	v_mfma_f32_16x16x32_bf16 v[26:29], v[2:5], v[10:13], 0
	ds_read_b128 v[30:33], v115
	ds_read_b128 v[34:37], v115 offset:2048
	s_add_u32 s74, s28, 0x30000
	s_addc_u32 s75, s29, 0
	v_mfma_f32_16x16x32_bf16 v[2:5], v[2:5], v[18:21], 0
	s_add_i32 s66, s30, 0xc000
	s_waitcnt lgkmcnt(1)
	v_mfma_f32_16x16x32_bf16 v[26:29], v[30:33], v[14:17], v[26:29]
	v_mfma_f32_16x16x32_bf16 v[2:5], v[30:33], v[22:25], v[2:5]
	v_mfma_f32_16x16x32_bf16 v[30:33], v[6:9], v[10:13], 0
	s_nop 5
	v_exp_f32_e32 v26, v26
	v_exp_f32_e32 v27, v27
	v_exp_f32_e32 v28, v28
	v_mfma_f32_16x16x32_bf16 v[6:9], v[6:9], v[18:21], 0
	v_exp_f32_e32 v29, v29
	v_exp_f32_e32 v2, v2
	v_exp_f32_e32 v3, v3
	s_waitcnt lgkmcnt(0)
	v_mfma_f32_16x16x32_bf16 v[30:33], v[34:37], v[14:17], v[30:33]
	v_exp_f32_e32 v4, v4
	v_exp_f32_e32 v5, v5
	v_cvt_pk_bf16_f32 v2, v2, v3
	v_mfma_f32_16x16x32_bf16 v[6:9], v[34:37], v[22:25], v[6:9]
	ds_read_b128 v[34:37], v1 offset:4096
	ds_read_b128 v[38:41], v1 offset:6144
	ds_read_b128 v[46:49], v115 offset:4096
	ds_read_b128 v[50:53], v115 offset:6144
	s_waitcnt vmcnt(0) lgkmcnt(0)
	s_barrier
; #define ATT_WAIT_BAR(N) asm volatile("s_waitcnt vmcnt(" #N ") lgkmcnt(0)\n\ts_barrier" ::: "memory")
; #define DMA_K(t, slot) do { _Pragma("unroll") for (int pc_ = 0; pc_ < NPK; ++pc_) glds16s(U.Kt + (size_t)(t) * 64 * U.KP + pc_ * 64, koff, (unsigned)__builtin_amdgcn_readfirstlane(kdst[pc_] + (slot) * KS)); } while (0)
; #define DMA_V(t, slot) do { _Pragma("unroll") for (int pc_ = 0; pc_ < NPV; ++pc_) glds16s(U.Vt + (size_t)(t) * 64 * U.VP + pc_ * 64, voff, (unsigned)__builtin_amdgcn_readfirstlane(vdst[pc_] + (slot) * VS)); } while (0)
; #define DMA_K(t, slot) do { _Pragma("unroll") for (int pc_ = 0; pc_ < NPK; ++pc_) glds16s(U.Kt + (size_t)(t) * 64 * U.KP + pc_ * 64, koff, (unsigned)__builtin_amdgcn_readfirstlane(kdst[pc_] + (slot) * KS)); } while (0)
; #define DMA_V(t, slot) do { _Pragma("unroll") for (int pc_ = 0; pc_ < NPV; ++pc_) glds16s(U.Vt + (size_t)(t) * 64 * U.VP + pc_ * 64, voff, (unsigned)__builtin_amdgcn_readfirstlane(vdst[pc_] + (slot) * VS)); } while (0)
; #define KRD16(j) do { kf[(j) >> 1][(j) & 1] = *(const __attribute__((address_space(3))) bf16x8*)(kpb[(j) & 1] + kn_ + ((j) >> 1) * 2048); } while (0)
; __device__ __forceinline__ void attn_unit_d16(const UnitDesc& U, char* shm, float lam, const float* subw) {
;     ...
;     for (int qt = 0; qt < 2; ++qt) { ls[qt] = zero4;
; #pragma unroll
;         for (int dt = 0; dt < 8; ++dt) o[qt][dt] = zero4; }
;     ...
;     DMA_K(3, 3); DMA_V(VAH, 2);
;     { const int kn_ = KS;
; #pragma unroll
;       for (int j = 0; j < 8; ++j) KRD16(j); }
;     ATT_WAIT_BAR(4);
	s_waitcnt lgkmcnt(3)
	v_mfma_f32_16x16x32_bf16 v[42:45], v[34:37], v[10:13], 0
	s_mov_b32 s67, m0
	s_mov_b32 m0, s66
	s_nop 0
	global_load_lds_dwordx4 v157, s[74:75]
	s_mov_b32 m0, s67
	s_add_u32 s74, s28, 0x30080
	s_addc_u32 s75, s29, 0
	v_mfma_f32_16x16x32_bf16 v[34:37], v[34:37], v[18:21], 0
	s_add_i32 s28, s31, 0xc000
	s_mov_b32 s29, m0
	s_mov_b32 m0, s28
	s_nop 0
	global_load_lds_dwordx4 v157, s[74:75]
	s_add_u32 s74, s74, 0xff80
	s_addc_u32 s75, s75, 0
	s_mov_b32 m0, s30
	s_nop 0
	global_load_lds_dwordx4 v157, s[74:75]
	s_add_u32 s74, s74, 0x80
	s_addc_u32 s75, s75, 0
	s_mov_b32 m0, s31
	s_nop 0
	global_load_lds_dwordx4 v157, s[74:75]
	s_mov_b32 m0, s29
	s_add_u32 s74, s10, 0x20000
	s_waitcnt lgkmcnt(1)
	v_mfma_f32_16x16x32_bf16 v[42:45], v[46:49], v[14:17], v[42:45]
	s_addc_u32 s75, s11, 0
	s_add_i32 s29, s38, 0x8000
	s_mov_b32 s67, m0
	s_mov_b32 m0, s29
	s_nop 0
	global_load_lds_dwordx4 v156, s[74:75]
	s_mov_b32 m0, s67
	v_mfma_f32_16x16x32_bf16 v[34:37], v[46:49], v[22:25], v[34:37]
	s_add_u32 s74, s10, 0x20080
	s_addc_u32 s75, s11, 0
	s_add_i32 s67, s39, 0x8000
	v_mfma_f32_16x16x32_bf16 v[46:49], v[38:41], v[10:13], 0
	s_mov_b32 s69, m0
	s_mov_b32 m0, s67
	s_nop 0
	global_load_lds_dwordx4 v156, s[74:75]
	s_mov_b32 m0, s69
	s_lshl_b32 s68, s68, 7
	s_lshl_b32 s33, s33, 7
	v_mfma_f32_16x16x32_bf16 v[38:41], v[38:41], v[18:21], 0
	v_exp_f32_e32 v32, v32
	v_exp_f32_e32 v33, v33
	s_sub_i32 s33, s68, s33
	s_waitcnt lgkmcnt(0)
	v_mfma_f32_16x16x32_bf16 v[46:49], v[50:53], v[14:17], v[46:49]
	v_exp_f32_e32 v30, v30
	v_exp_f32_e32 v31, v31
	v_exp_f32_e32 v42, v42
	v_mfma_f32_16x16x32_bf16 v[38:41], v[50:53], v[22:25], v[38:41]
	v_exp_f32_e32 v50, v6
	v_exp_f32_e32 v51, v7
	v_cvt_pk_bf16_f32 v6, v26, v27
	v_cvt_pk_bf16_f32 v7, v28, v29
	ds_read_b128 v[110:113], v1 offset:16384
	ds_read_b128 v[116:119], v1 offset:18432
	ds_read_b128 v[26:29], v115 offset:16384
	ds_read_b128 v[120:123], v115 offset:18432
	ds_read_b128 v[124:127], v1 offset:20480
	ds_read_b128 v[128:131], v1 offset:22528
	ds_read_b128 v[132:135], v115 offset:20480
	ds_read_b128 v[136:139], v115 offset:22528
	v_exp_f32_e32 v38, v38
	v_exp_f32_e32 v39, v39
	v_exp_f32_e32 v52, v8
	v_exp_f32_e32 v53, v9
	v_exp_f32_e32 v43, v43
	v_exp_f32_e32 v44, v44
	v_exp_f32_e32 v45, v45
	v_exp_f32_e32 v54, v34
	v_exp_f32_e32 v55, v35
	v_exp_f32_e32 v56, v36
	v_exp_f32_e32 v57, v37
	v_exp_f32_e32 v36, v46
	v_exp_f32_e32 v37, v47
	v_exp_f32_e32 v46, v48
	v_exp_f32_e32 v47, v49
	v_exp_f32_e32 v40, v40
	v_exp_f32_e32 v41, v41
	s_lshl_b32 s33, s33, 1
	s_and_b32 s33, s33, 0x300
	s_waitcnt vmcnt(6) lgkmcnt(0)
	s_barrier
	s_or_b32 s14, s14, s33
	v_cvt_pk_bf16_f32 v9, v32, v33
	v_cvt_pk_bf16_f32 v32, v38, v39
	s_add_u32 s14, s3, s14
	v_mov_b32_e32 v38, 0
	v_cvt_pk_bf16_f32 v8, v30, v31
	v_cvt_pk_bf16_f32 v34, v42, v43
	v_cvt_pk_bf16_f32 v35, v44, v45
	v_cvt_pk_bf16_f32 v36, v36, v37
	v_cvt_pk_bf16_f32 v37, v46, v47
	v_cvt_pk_bf16_f32 v3, v4, v5
	v_cvt_pk_bf16_f32 v4, v50, v51
	v_cvt_pk_bf16_f32 v5, v52, v53
	v_cvt_pk_bf16_f32 v30, v54, v55
	v_cvt_pk_bf16_f32 v31, v56, v57
	v_cvt_pk_bf16_f32 v33, v40, v41
	s_addc_u32 s15, s44, s15
	s_mov_b32 s33, -3
	v_mov_b32_e32 v39, v38
	v_mov_b32_e32 v40, v38
	v_mov_b32_e32 v41, v38
	v_mov_b32_e32 v42, v38
	v_mov_b32_e32 v43, v38
	v_mov_b32_e32 v44, v38
	v_mov_b32_e32 v45, v38
	v_mov_b32_e32 v50, v38
	v_mov_b32_e32 v51, v38
	v_mov_b32_e32 v52, v38
	v_mov_b32_e32 v53, v38
	v_mov_b32_e32 v58, v38
	v_mov_b32_e32 v59, v38
	v_mov_b32_e32 v60, v38
	v_mov_b32_e32 v61, v38
	v_mov_b32_e32 v66, v38
	v_mov_b32_e32 v67, v38
	v_mov_b32_e32 v68, v38
	v_mov_b32_e32 v69, v38
	v_mov_b32_e32 v74, v38
	v_mov_b32_e32 v75, v38
	v_mov_b32_e32 v76, v38
	v_mov_b32_e32 v77, v38
	v_mov_b32_e32 v82, v38
	v_mov_b32_e32 v83, v38
	v_mov_b32_e32 v84, v38
	v_mov_b32_e32 v85, v38
	v_mov_b32_e32 v90, v38
	v_mov_b32_e32 v91, v38
	v_mov_b32_e32 v92, v38
	v_mov_b32_e32 v93, v38
	v_mov_b32_e32 v46, v38
	v_mov_b32_e32 v47, v38
	v_mov_b32_e32 v48, v38
	v_mov_b32_e32 v49, v38
	v_mov_b32_e32 v54, v38
	v_mov_b32_e32 v55, v38
	v_mov_b32_e32 v56, v38
	v_mov_b32_e32 v57, v38
	v_mov_b32_e32 v62, v38
	v_mov_b32_e32 v63, v38
	v_mov_b32_e32 v64, v38
	v_mov_b32_e32 v65, v38
	v_mov_b32_e32 v70, v38
	v_mov_b32_e32 v71, v38
	v_mov_b32_e32 v72, v38
	v_mov_b32_e32 v73, v38
	v_mov_b32_e32 v78, v38
	v_mov_b32_e32 v79, v38
	v_mov_b32_e32 v80, v38
	v_mov_b32_e32 v81, v38
	v_mov_b32_e32 v86, v38
	v_mov_b32_e32 v87, v38
	v_mov_b32_e32 v88, v38
	v_mov_b32_e32 v89, v38
	v_mov_b32_e32 v94, v38
	v_mov_b32_e32 v95, v38
	v_mov_b32_e32 v96, v38
	v_mov_b32_e32 v97, v38
	v_mov_b32_e32 v98, v38
	v_mov_b32_e32 v99, v38
	v_mov_b32_e32 v100, v38
	v_mov_b32_e32 v101, v38
	v_mov_b32_e32 v102, v38
	v_mov_b32_e32 v103, v38
	v_mov_b32_e32 v104, v38
	v_mov_b32_e32 v105, v38
	v_mov_b32_e32 v106, v38
	v_mov_b32_e32 v107, v38
	v_mov_b32_e32 v108, v38
	v_mov_b32_e32 v109, v38
; #define ATT_WAIT_BARV(N) asm volatile("s_waitcnt vmcnt(" #N ")\n\ts_barrier" ::: "memory")
; __device__ __forceinline__ void attn_unit_d16(const UnitDesc& U, char* shm, float lam, const float* subw) {
;     ...
;     for (int t = 1; t <= NT - 4; t += 4) {
;         STEP_D16(t, true, true, true, 1, 2, 0, 0, 3);     ATT_WAIT_BARV(4);
.LBB0_444:
	ds_read_b64_tr_b16 v[158:159], v203
	ds_read_b64_tr_b16 v[160:161], v203 offset:2048
	s_waitcnt lgkmcnt(9)
	v_mfma_f32_16x16x32_bf16 v[140:143], v[110:113], v[10:13], 0
	s_waitcnt lgkmcnt(7)
	v_mfma_f32_16x16x32_bf16 v[152:155], v[26:29], v[14:17], v[140:143]
	ds_read_b64_tr_b16 v[162:163], v204
	ds_read_b64_tr_b16 v[164:165], v204 offset:2048
	v_mfma_f32_16x16x32_bf16 v[110:113], v[110:113], v[18:21], 0
	v_mfma_f32_16x16x32_bf16 v[144:147], v[26:29], v[22:25], v[110:113]
	ds_read_b64_tr_b16 v[166:167], v205
	ds_read_b64_tr_b16 v[168:169], v205 offset:2048
	v_mfma_f32_16x16x32_bf16 v[26:29], v[116:119], v[10:13], 0
	s_waitcnt lgkmcnt(10)
	v_mfma_f32_16x16x32_bf16 v[148:151], v[120:123], v[14:17], v[26:29]
	ds_read_b64_tr_b16 v[170:171], v206
	ds_read_b64_tr_b16 v[172:173], v206 offset:2048
	v_mfma_f32_16x16x32_bf16 v[26:29], v[116:119], v[18:21], 0
	v_mfma_f32_16x16x32_bf16 v[140:143], v[120:123], v[22:25], v[26:29]
	ds_read_b64_tr_b16 v[174:175], v203 offset:8192
	ds_read_b64_tr_b16 v[176:177], v203 offset:10240
	s_waitcnt lgkmcnt(13)
	v_mfma_f32_16x16x32_bf16 v[26:29], v[124:127], v[10:13], 0
	s_waitcnt lgkmcnt(11)
	v_mfma_f32_16x16x32_bf16 v[110:113], v[132:135], v[14:17], v[26:29]
	ds_read_b64_tr_b16 v[208:209], v204 offset:8192
	ds_read_b64_tr_b16 v[210:211], v204 offset:10240
	v_mfma_f32_16x16x32_bf16 v[26:29], v[124:127], v[18:21], 0
	v_mfma_f32_16x16x32_bf16 v[116:119], v[132:135], v[22:25], v[26:29]
	ds_read_b64_tr_b16 v[132:133], v205 offset:8192
	ds_read_b64_tr_b16 v[134:135], v205 offset:10240
	v_mfma_f32_16x16x32_bf16 v[26:29], v[128:131], v[10:13], 0
	s_waitcnt lgkmcnt(14)
	v_mfma_f32_16x16x32_bf16 v[120:123], v[136:139], v[14:17], v[26:29]
	ds_read_b64_tr_b16 v[212:213], v206 offset:8192
	ds_read_b64_tr_b16 v[214:215], v206 offset:10240
	v_mfma_f32_16x16x32_bf16 v[26:29], v[128:131], v[18:21], 0
	v_mfma_f32_16x16x32_bf16 v[124:127], v[136:139], v[22:25], v[26:29]
	s_add_u32 s68, s14, 0xfcff0000
	s_addc_u32 s69, s15, -1
	s_mov_b32 s74, m0
	s_mov_b32 m0, s40
	s_nop 0
	global_load_lds_dwordx4 v157, s[68:69]
	s_mov_b32 m0, s74
	s_add_u32 s68, s14, 0xfcff0080
	s_addc_u32 s69, s15, -1
	s_mov_b32 s74, m0
	s_mov_b32 m0, s41
	s_nop 0
	global_load_lds_dwordx4 v157, s[68:69]
	s_mov_b32 m0, s74
	s_add_u32 s74, s14, 0xfffd0000
	s_addc_u32 s75, s15, -1
	s_add_i32 s68, s38, 0xc000
	s_mov_b32 s69, m0
	s_mov_b32 m0, s68
	s_nop 0
	global_load_lds_dwordx4 v156, s[74:75]
	s_mov_b32 m0, s69
	s_add_u32 s74, s14, 0xfffd0080
	s_addc_u32 s75, s15, -1
	s_add_i32 s69, s39, 0xc000
	s_mov_b32 s76, m0
	s_mov_b32 m0, s69
	s_nop 0
	global_load_lds_dwordx4 v156, s[74:75]
	s_mov_b32 m0, s76
	ds_read_b64_tr_b16 v[128:129], v203 offset:4096
	ds_read_b64_tr_b16 v[130:131], v203 offset:6144
	v_mov_b64_e32 v[28:29], s[6:7]
	v_mov_b64_e32 v[26:27], s[4:5]
	s_waitcnt lgkmcnt(14)
	v_mfma_f32_16x16x32_bf16 v[98:101], v[6:9], v[158:161], v[98:101]
	v_exp_f32_e32 v152, v152
	v_mfma_f32_16x16x32_bf16 v[106:109], v[6:9], v[26:29], v[106:109]
	v_mfma_f32_16x16x32_bf16 v[102:105], v[2:5], v[26:29], v[102:105]
	v_exp_f32_e32 v153, v153
	v_mfma_f32_16x16x32_bf16 v[90:93], v[2:5], v[158:161], v[90:93]
	ds_read_b64_tr_b16 v[136:137], v204 offset:4096
	ds_read_b64_tr_b16 v[138:139], v204 offset:6144
	v_mfma_f32_16x16x32_bf16 v[94:97], v[6:9], v[162:165], v[94:97]
	v_exp_f32_e32 v154, v154
	v_mfma_f32_16x16x32_bf16 v[82:85], v[2:5], v[162:165], v[82:85]
	v_exp_f32_e32 v155, v155
	ds_read_b64_tr_b16 v[158:159], v205 offset:4096
	ds_read_b64_tr_b16 v[160:161], v205 offset:6144
	s_waitcnt lgkmcnt(14)
	v_mfma_f32_16x16x32_bf16 v[86:89], v[6:9], v[166:169], v[86:89]
	v_exp_f32_e32 v144, v144
	s_nop 0
	v_exp_f32_e32 v145, v145
	v_mfma_f32_16x16x32_bf16 v[162:165], v[2:5], v[166:169], v[74:77]
	ds_read_b64_tr_b16 v[166:167], v206 offset:4096
	ds_read_b64_tr_b16 v[168:169], v206 offset:6144
	v_exp_f32_e32 v146, v146
	v_mfma_f32_16x16x32_bf16 v[216:219], v[6:9], v[170:173], v[78:81]
	s_nop 0
	v_exp_f32_e32 v147, v147
	v_mfma_f32_16x16x32_bf16 v[170:173], v[2:5], v[170:173], v[66:69]
	ds_read_b64_tr_b16 v[220:221], v203 offset:12288
	ds_read_b64_tr_b16 v[222:223], v203 offset:14336
	v_exp_f32_e32 v148, v148
	s_waitcnt lgkmcnt(14)
	v_mfma_f32_16x16x32_bf16 v[224:227], v[6:9], v[174:177], v[70:73]
	v_mfma_f32_16x16x32_bf16 v[58:61], v[2:5], v[174:177], v[58:61]
	v_exp_f32_e32 v149, v149
	ds_read_b64_tr_b16 v[174:175], v204 offset:12288
	ds_read_b64_tr_b16 v[176:177], v204 offset:14336
	v_exp_f32_e32 v150, v150
	v_mfma_f32_16x16x32_bf16 v[228:231], v[6:9], v[208:211], v[62:65]
	v_mfma_f32_16x16x32_bf16 v[50:53], v[2:5], v[208:211], v[50:53]
	v_exp_f32_e32 v151, v151
	ds_read_b64_tr_b16 v[208:209], v205 offset:12288
	ds_read_b64_tr_b16 v[210:211], v205 offset:14336
	s_waitcnt lgkmcnt(14)
	v_mfma_f32_16x16x32_bf16 v[54:57], v[6:9], v[132:135], v[54:57]
	v_exp_f32_e32 v140, v140
	v_mfma_f32_16x16x32_bf16 v[42:45], v[2:5], v[132:135], v[42:45]
	v_exp_f32_e32 v141, v141
	ds_read_b64_tr_b16 v[232:233], v206 offset:12288
	ds_read_b64_tr_b16 v[234:235], v206 offset:14336
	v_mfma_f32_16x16x32_bf16 v[46:49], v[6:9], v[212:215], v[46:49]
	v_exp_f32_e32 v142, v142
	s_nop 0
	v_exp_f32_e32 v143, v143
	v_mfma_f32_16x16x32_bf16 v[212:215], v[2:5], v[212:215], v[38:41]
	s_nop 2
	ds_read_b128 v[38:41], v1 offset:32768
	v_mfma_f32_16x16x32_bf16 v[66:69], v[34:37], v[26:29], v[106:109]
	v_exp_f32_e32 v110, v110
	v_cvt_pk_bf16_f32 v6, v152, v153
	s_waitcnt lgkmcnt(14)
	v_mfma_f32_16x16x32_bf16 v[62:65], v[34:37], v[128:131], v[98:101]
	v_mfma_f32_16x16x32_bf16 v[70:73], v[30:33], v[26:29], v[102:105]
	v_exp_f32_e32 v111, v111
	v_cvt_pk_bf16_f32 v7, v154, v155
	v_mfma_f32_16x16x32_bf16 v[78:81], v[30:33], v[128:131], v[90:93]
	ds_read_b128 v[236:239], v115 offset:32768
	s_waitcnt lgkmcnt(14)
; #define ATT_WAIT_BARV(N) asm volatile("s_waitcnt vmcnt(" #N ")\n\ts_barrier" ::: "memory")
; __device__ __forceinline__ void attn_unit_d16(const UnitDesc& U, char* shm, float lam, const float* subw) {
;     ...
;     for (int t = 1; t <= NT - 4; t += 4) {
;         STEP_D16(t, true, true, true, 1, 2, 0, 0, 3);     ATT_WAIT_BARV(4);
;         STEP_D16(t + 1, true, true, true, 2, 3, 1, 1, 0); ATT_WAIT_BARV(4);
	v_mfma_f32_16x16x32_bf16 v[74:77], v[34:37], v[136:139], v[94:97]
	v_exp_f32_e32 v112, v112
	v_cvt_pk_bf16_f32 v8, v148, v149
	v_mfma_f32_16x16x32_bf16 v[82:85], v[30:33], v[136:139], v[82:85]
	v_exp_f32_e32 v113, v113
	v_cvt_pk_bf16_f32 v9, v150, v151
	ds_read_b128 v[240:243], v1 offset:34816
	s_waitcnt lgkmcnt(13)
	v_mfma_f32_16x16x32_bf16 v[90:93], v[34:37], v[158:161], v[86:89]
	v_exp_f32_e32 v116, v116
	v_cvt_pk_bf16_f32 v2, v144, v145
	v_mfma_f32_16x16x32_bf16 v[94:97], v[30:33], v[158:161], v[162:165]
	v_exp_f32_e32 v117, v117
	v_cvt_pk_bf16_f32 v3, v146, v147
	ds_read_b128 v[158:161], v115 offset:34816
	s_waitcnt lgkmcnt(12)
	v_mfma_f32_16x16x32_bf16 v[98:101], v[34:37], v[166:169], v[216:219]
	v_exp_f32_e32 v118, v118
	v_cvt_pk_bf16_f32 v4, v140, v141
	v_mfma_f32_16x16x32_bf16 v[102:105], v[30:33], v[166:169], v[170:173]
	v_exp_f32_e32 v119, v119
	v_cvt_pk_bf16_f32 v5, v142, v143
	ds_read_b128 v[162:165], v1 offset:36864
	v_exp_f32_e32 v120, v120
	s_waitcnt lgkmcnt(11)
	v_mfma_f32_16x16x32_bf16 v[148:151], v[34:37], v[220:223], v[224:227]
	s_nop 0
	v_exp_f32_e32 v121, v121
	v_mfma_f32_16x16x32_bf16 v[152:155], v[30:33], v[220:223], v[58:61]
	ds_read_b128 v[166:169], v115 offset:36864
	v_exp_f32_e32 v122, v122
	s_waitcnt lgkmcnt(10)
	v_mfma_f32_16x16x32_bf16 v[140:143], v[34:37], v[174:177], v[228:231]
	s_nop 0
	v_exp_f32_e32 v123, v123
	v_mfma_f32_16x16x32_bf16 v[144:147], v[30:33], v[174:177], v[50:53]
	s_nop 2
	ds_read_b128 v[50:53], v1 offset:38912
	s_waitcnt lgkmcnt(9)
	v_mfma_f32_16x16x32_bf16 v[132:135], v[34:37], v[208:211], v[54:57]
	v_exp_f32_e32 v124, v124
	v_mfma_f32_16x16x32_bf16 v[136:139], v[30:33], v[208:211], v[42:45]
	v_exp_f32_e32 v125, v125
	ds_read_b128 v[170:173], v115 offset:38912
	s_waitcnt lgkmcnt(8)
	v_mfma_f32_16x16x32_bf16 v[106:109], v[34:37], v[232:235], v[46:49]
	v_exp_f32_e32 v126, v126
	v_mfma_f32_16x16x32_bf16 v[128:131], v[30:33], v[232:235], v[212:215]
	v_exp_f32_e32 v127, v127
	v_cvt_pk_bf16_f32 v34, v110, v111
	v_cvt_pk_bf16_f32 v35, v112, v113
	v_cvt_pk_bf16_f32 v36, v120, v121
	v_cvt_pk_bf16_f32 v37, v122, v123
	v_cvt_pk_bf16_f32 v30, v116, v117
	v_cvt_pk_bf16_f32 v31, v118, v119
	v_cvt_pk_bf16_f32 v32, v124, v125
	v_cvt_pk_bf16_f32 v33, v126, v127
	s_waitcnt vmcnt(8)
	s_barrier
	ds_read_b64_tr_b16 v[116:117], v203 offset:16384
	ds_read_b64_tr_b16 v[118:119], v203 offset:18432
	s_waitcnt lgkmcnt(9)
	v_mfma_f32_16x16x32_bf16 v[42:45], v[38:41], v[10:13], 0
	s_waitcnt lgkmcnt(8)
	v_mfma_f32_16x16x32_bf16 v[110:113], v[236:239], v[14:17], v[42:45]
	ds_read_b64_tr_b16 v[120:121], v204 offset:16384
	ds_read_b64_tr_b16 v[122:123], v204 offset:18432
	v_mfma_f32_16x16x32_bf16 v[38:41], v[38:41], v[18:21], 0
	v_mfma_f32_16x16x32_bf16 v[58:61], v[236:239], v[22:25], v[38:41]
	ds_read_b64_tr_b16 v[124:125], v205 offset:16384
	ds_read_b64_tr_b16 v[126:127], v205 offset:18432
	s_waitcnt lgkmcnt(11)
	v_mfma_f32_16x16x32_bf16 v[38:41], v[240:243], v[10:13], 0
	s_waitcnt lgkmcnt(10)
	v_mfma_f32_16x16x32_bf16 v[86:89], v[158:161], v[14:17], v[38:41]
	ds_read_b64_tr_b16 v[174:175], v206 offset:16384
	ds_read_b64_tr_b16 v[176:177], v206 offset:18432
	v_mfma_f32_16x16x32_bf16 v[38:41], v[240:243], v[18:21], 0
	v_mfma_f32_16x16x32_bf16 v[54:57], v[158:161], v[22:25], v[38:41]
	ds_read_b64_tr_b16 v[158:159], v203 offset:24576
	ds_read_b64_tr_b16 v[160:161], v203 offset:26624
	s_waitcnt lgkmcnt(13)
	v_mfma_f32_16x16x32_bf16 v[38:41], v[162:165], v[10:13], 0
	s_waitcnt lgkmcnt(12)
	v_mfma_f32_16x16x32_bf16 v[38:41], v[166:169], v[14:17], v[38:41]
	ds_read_b64_tr_b16 v[208:209], v204 offset:24576
	ds_read_b64_tr_b16 v[210:211], v204 offset:26624
	v_mfma_f32_16x16x32_bf16 v[42:45], v[162:165], v[18:21], 0
	v_mfma_f32_16x16x32_bf16 v[42:45], v[166:169], v[22:25], v[42:45]
	ds_read_b64_tr_b16 v[162:163], v205 offset:24576
	ds_read_b64_tr_b16 v[164:165], v205 offset:26624
	s_waitcnt lgkmcnt(14)
	v_mfma_f32_16x16x32_bf16 v[46:49], v[50:53], v[10:13], 0
	v_mfma_f32_16x16x32_bf16 v[46:49], v[170:173], v[14:17], v[46:49]
	ds_read_b64_tr_b16 v[166:167], v206 offset:24576
	ds_read_b64_tr_b16 v[168:169], v206 offset:26624
	v_mfma_f32_16x16x32_bf16 v[50:53], v[50:53], v[18:21], 0
	v_mfma_f32_16x16x32_bf16 v[50:53], v[170:173], v[22:25], v[50:53]
	s_add_u32 s74, s14, 0xfd000000
	s_addc_u32 s75, s15, -1
	s_mov_b32 s76, m0
	s_mov_b32 m0, s52
	s_nop 0
	global_load_lds_dwordx4 v157, s[74:75]
	s_mov_b32 m0, s76
	s_add_u32 s74, s14, 0xfd000080
	s_addc_u32 s75, s15, -1
	s_mov_b32 s76, m0
	s_mov_b32 m0, s53
	s_nop 0
	global_load_lds_dwordx4 v157, s[74:75]
	s_mov_b32 m0, s76
	s_add_u32 s74, s14, 0xfffe0000
	s_addc_u32 s75, s15, -1
	s_mov_b32 s76, m0
	s_mov_b32 m0, s38
	s_nop 0
	global_load_lds_dwordx4 v156, s[74:75]
	s_mov_b32 m0, s76
	s_add_u32 s74, s14, 0xfffe0080
	s_addc_u32 s75, s15, -1
	s_mov_b32 s76, m0
	s_mov_b32 m0, s39
	s_nop 0
	global_load_lds_dwordx4 v156, s[74:75]
	s_mov_b32 m0, s76
	ds_read_b64_tr_b16 v[170:171], v203 offset:20480
	ds_read_b64_tr_b16 v[172:173], v203 offset:22528
	v_mfma_f32_16x16x32_bf16 v[66:69], v[6:9], v[26:29], v[66:69]
	v_exp_f32_e32 v110, v110
	s_waitcnt lgkmcnt(14)
	v_mfma_f32_16x16x32_bf16 v[62:65], v[6:9], v[116:119], v[62:65]
	v_mfma_f32_16x16x32_bf16 v[70:73], v[2:5], v[26:29], v[70:73]
	v_exp_f32_e32 v111, v111
	v_mfma_f32_16x16x32_bf16 v[78:81], v[2:5], v[116:119], v[78:81]
	ds_read_b64_tr_b16 v[116:117], v204 offset:20480
	ds_read_b64_tr_b16 v[118:119], v204 offset:22528
	v_mfma_f32_16x16x32_bf16 v[74:77], v[6:9], v[120:123], v[74:77]
	v_exp_f32_e32 v112, v112
	v_mfma_f32_16x16x32_bf16 v[82:85], v[2:5], v[120:123], v[82:85]
	v_exp_f32_e32 v113, v113
	ds_read_b64_tr_b16 v[120:121], v205 offset:20480
	ds_read_b64_tr_b16 v[122:123], v205 offset:22528
	s_waitcnt lgkmcnt(14)
; #define ATT_WAIT_BARV(N) asm volatile("s_waitcnt vmcnt(" #N ")\n\ts_barrier" ::: "memory")
; __device__ __forceinline__ void attn_unit_d16(const UnitDesc& U, char* shm, float lam, const float* subw) {
;     ...
;         STEP_D16(t + 1, true, true, true, 2, 3, 1, 1, 0); ATT_WAIT_BARV(4);
	v_mfma_f32_16x16x32_bf16 v[90:93], v[6:9], v[124:127], v[90:93]
	v_exp_f32_e32 v58, v58
	v_mfma_f32_16x16x32_bf16 v[94:97], v[2:5], v[124:127], v[94:97]
	v_exp_f32_e32 v59, v59
	ds_read_b64_tr_b16 v[124:125], v206 offset:20480
	ds_read_b64_tr_b16 v[126:127], v206 offset:22528
	v_mfma_f32_16x16x32_bf16 v[98:101], v[6:9], v[174:177], v[98:101]
	v_exp_f32_e32 v60, v60
	v_mfma_f32_16x16x32_bf16 v[102:105], v[2:5], v[174:177], v[102:105]
	v_exp_f32_e32 v61, v61
	ds_read_b64_tr_b16 v[174:175], v203 offset:28672
	ds_read_b64_tr_b16 v[176:177], v203 offset:30720
	v_exp_f32_e32 v86, v86
	s_waitcnt lgkmcnt(14)
	v_mfma_f32_16x16x32_bf16 v[148:151], v[6:9], v[158:161], v[148:151]
	s_nop 0
	v_exp_f32_e32 v87, v87
	v_mfma_f32_16x16x32_bf16 v[152:155], v[2:5], v[158:161], v[152:155]
	ds_read_b64_tr_b16 v[158:159], v204 offset:28672
	ds_read_b64_tr_b16 v[160:161], v204 offset:30720
	v_exp_f32_e32 v88, v88
	v_mfma_f32_16x16x32_bf16 v[212:215], v[6:9], v[208:211], v[140:143]
	s_nop 0
	v_exp_f32_e32 v89, v89
	v_mfma_f32_16x16x32_bf16 v[208:211], v[2:5], v[208:211], v[144:147]
	ds_read_b64_tr_b16 v[216:217], v205 offset:28672
	ds_read_b64_tr_b16 v[218:219], v205 offset:30720
	v_exp_f32_e32 v54, v54
	s_waitcnt lgkmcnt(14)
	v_mfma_f32_16x16x32_bf16 v[220:223], v[6:9], v[162:165], v[132:135]
	s_nop 0
	v_exp_f32_e32 v55, v55
	v_mfma_f32_16x16x32_bf16 v[162:165], v[2:5], v[162:165], v[136:139]
	ds_read_b64_tr_b16 v[224:225], v206 offset:28672
	ds_read_b64_tr_b16 v[226:227], v206 offset:30720
	v_mfma_f32_16x16x32_bf16 v[106:109], v[6:9], v[166:169], v[106:109]
	v_exp_f32_e32 v56, v56
	s_nop 0
	v_exp_f32_e32 v57, v57
	v_mfma_f32_16x16x32_bf16 v[166:169], v[2:5], v[166:169], v[128:131]
	ds_read_b128 v[144:147], v1 offset:49152
	v_mfma_f32_16x16x32_bf16 v[66:69], v[34:37], v[26:29], v[66:69]
	v_exp_f32_e32 v38, v38
	v_cvt_pk_bf16_f32 v6, v110, v111
	s_waitcnt lgkmcnt(14)
	v_mfma_f32_16x16x32_bf16 v[62:65], v[34:37], v[170:173], v[62:65]
	v_mfma_f32_16x16x32_bf16 v[70:73], v[30:33], v[26:29], v[70:73]
	v_exp_f32_e32 v39, v39
	v_cvt_pk_bf16_f32 v7, v112, v113
	v_mfma_f32_16x16x32_bf16 v[78:81], v[30:33], v[170:173], v[78:81]
	ds_read_b128 v[170:173], v115 offset:49152
	s_waitcnt lgkmcnt(14)
	v_mfma_f32_16x16x32_bf16 v[74:77], v[34:37], v[116:119], v[74:77]
	v_exp_f32_e32 v40, v40
	v_cvt_pk_bf16_f32 v8, v86, v87
	v_mfma_f32_16x16x32_bf16 v[82:85], v[30:33], v[116:119], v[82:85]
	v_exp_f32_e32 v41, v41
	v_cvt_pk_bf16_f32 v9, v88, v89
	ds_read_b128 v[228:231], v1 offset:51200
	s_waitcnt lgkmcnt(13)
	v_mfma_f32_16x16x32_bf16 v[90:93], v[34:37], v[120:123], v[90:93]
	v_exp_f32_e32 v42, v42
	v_cvt_pk_bf16_f32 v2, v58, v59
	v_mfma_f32_16x16x32_bf16 v[94:97], v[30:33], v[120:123], v[94:97]
	v_exp_f32_e32 v43, v43
	v_cvt_pk_bf16_f32 v3, v60, v61
	ds_read_b128 v[232:235], v115 offset:51200
	s_waitcnt lgkmcnt(12)
	v_mfma_f32_16x16x32_bf16 v[98:101], v[34:37], v[124:127], v[98:101]
	v_exp_f32_e32 v44, v44
	v_cvt_pk_bf16_f32 v4, v54, v55
	v_mfma_f32_16x16x32_bf16 v[102:105], v[30:33], v[124:127], v[102:105]
	v_exp_f32_e32 v45, v45
	v_cvt_pk_bf16_f32 v5, v56, v57
	ds_read_b128 v[236:239], v1 offset:53248
	s_waitcnt lgkmcnt(11)
	v_mfma_f32_16x16x32_bf16 v[136:139], v[34:37], v[174:177], v[148:151]
	v_exp_f32_e32 v46, v46
	s_nop 0
	v_exp_f32_e32 v47, v47
	v_mfma_f32_16x16x32_bf16 v[140:143], v[30:33], v[174:177], v[152:155]
	ds_read_b128 v[148:151], v115 offset:53248
	s_waitcnt lgkmcnt(10)
	v_mfma_f32_16x16x32_bf16 v[128:131], v[34:37], v[158:161], v[212:215]
	v_exp_f32_e32 v48, v48
	v_mfma_f32_16x16x32_bf16 v[132:135], v[30:33], v[158:161], v[208:211]
	v_exp_f32_e32 v49, v49
	ds_read_b128 v[152:155], v1 offset:55296
	s_waitcnt lgkmcnt(9)
	v_mfma_f32_16x16x32_bf16 v[120:123], v[34:37], v[216:219], v[220:223]
	v_exp_f32_e32 v50, v50
	v_mfma_f32_16x16x32_bf16 v[124:127], v[30:33], v[216:219], v[162:165]
	v_exp_f32_e32 v51, v51
	ds_read_b128 v[158:161], v115 offset:55296
	s_waitcnt lgkmcnt(8)
	v_mfma_f32_16x16x32_bf16 v[106:109], v[34:37], v[224:227], v[106:109]
	v_exp_f32_e32 v52, v52
	v_mfma_f32_16x16x32_bf16 v[110:113], v[30:33], v[224:227], v[166:169]
	v_exp_f32_e32 v53, v53
	v_cvt_pk_bf16_f32 v34, v38, v39
	v_cvt_pk_bf16_f32 v35, v40, v41
	v_cvt_pk_bf16_f32 v36, v46, v47
	v_cvt_pk_bf16_f32 v37, v48, v49
	v_cvt_pk_bf16_f32 v30, v42, v43
	v_cvt_pk_bf16_f32 v31, v44, v45
	v_cvt_pk_bf16_f32 v32, v50, v51
	v_cvt_pk_bf16_f32 v33, v52, v53
	s_waitcnt vmcnt(8)
	s_barrier
; #define ATT_WAIT_BARV(N) asm volatile("s_waitcnt vmcnt(" #N ")\n\ts_barrier" ::: "memory")
; __device__ __forceinline__ void attn_unit_d16(const UnitDesc& U, char* shm, float lam, const float* subw) {
;     ...
;         STEP_D16(t + 1, true, true, true, 2, 3, 1, 1, 0); ATT_WAIT_BARV(4);
;         STEP_D16(t + 2, true, true, true, 3, 0, 2, 2, 1); ATT_WAIT_BARV(4);
	ds_read_b64_tr_b16 v[162:163], v203 offset:32768
	ds_read_b64_tr_b16 v[164:165], v203 offset:34816
	s_waitcnt lgkmcnt(9)
	v_mfma_f32_16x16x32_bf16 v[38:41], v[144:147], v[10:13], 0
	s_waitcnt lgkmcnt(8)
	v_mfma_f32_16x16x32_bf16 v[116:119], v[170:173], v[14:17], v[38:41]
	ds_read_b64_tr_b16 v[166:167], v204 offset:32768
	ds_read_b64_tr_b16 v[168:169], v204 offset:34816
	v_mfma_f32_16x16x32_bf16 v[38:41], v[144:147], v[18:21], 0
	v_mfma_f32_16x16x32_bf16 v[58:61], v[170:173], v[22:25], v[38:41]
	ds_read_b64_tr_b16 v[144:145], v205 offset:32768
	ds_read_b64_tr_b16 v[146:147], v205 offset:34816
	s_waitcnt lgkmcnt(11)
	v_mfma_f32_16x16x32_bf16 v[38:41], v[228:231], v[10:13], 0
	s_waitcnt lgkmcnt(10)
	v_mfma_f32_16x16x32_bf16 v[86:89], v[232:235], v[14:17], v[38:41]
	ds_read_b64_tr_b16 v[170:171], v206 offset:32768
	ds_read_b64_tr_b16 v[172:173], v206 offset:34816
	v_mfma_f32_16x16x32_bf16 v[38:41], v[228:231], v[18:21], 0
	v_mfma_f32_16x16x32_bf16 v[54:57], v[232:235], v[22:25], v[38:41]
	ds_read_b64_tr_b16 v[174:175], v203 offset:40960
	ds_read_b64_tr_b16 v[176:177], v203 offset:43008
	s_waitcnt lgkmcnt(13)
	v_mfma_f32_16x16x32_bf16 v[38:41], v[236:239], v[10:13], 0
	s_waitcnt lgkmcnt(12)
	v_mfma_f32_16x16x32_bf16 v[38:41], v[148:151], v[14:17], v[38:41]
	ds_read_b64_tr_b16 v[208:209], v204 offset:40960
	ds_read_b64_tr_b16 v[210:211], v204 offset:43008
	v_mfma_f32_16x16x32_bf16 v[42:45], v[236:239], v[18:21], 0
	v_mfma_f32_16x16x32_bf16 v[42:45], v[148:151], v[22:25], v[42:45]
	ds_read_b64_tr_b16 v[148:149], v205 offset:40960
	ds_read_b64_tr_b16 v[150:151], v205 offset:43008
	s_waitcnt lgkmcnt(14)
	v_mfma_f32_16x16x32_bf16 v[46:49], v[152:155], v[10:13], 0
	v_mfma_f32_16x16x32_bf16 v[46:49], v[158:161], v[14:17], v[46:49]
	ds_read_b64_tr_b16 v[212:213], v206 offset:40960
	ds_read_b64_tr_b16 v[214:215], v206 offset:43008
	v_mfma_f32_16x16x32_bf16 v[50:53], v[152:155], v[18:21], 0
	v_mfma_f32_16x16x32_bf16 v[50:53], v[158:161], v[22:25], v[50:53]
	s_add_u32 s74, s14, 0xfd010000
	s_addc_u32 s75, s15, -1
	s_mov_b32 s76, m0
	s_mov_b32 m0, s66
	s_nop 0
	global_load_lds_dwordx4 v157, s[74:75]
	s_mov_b32 m0, s76
	s_add_u32 s74, s14, 0xfd010080
	s_addc_u32 s75, s15, -1
	s_mov_b32 s76, m0
	s_mov_b32 m0, s28
	s_nop 0
	global_load_lds_dwordx4 v157, s[74:75]
	s_mov_b32 m0, s76
	s_add_u32 s74, s14, 0xffff0000
	s_addc_u32 s75, s15, -1
	s_mov_b32 s76, m0
	s_mov_b32 m0, s62
	s_nop 0
	global_load_lds_dwordx4 v156, s[74:75]
	s_mov_b32 m0, s76
	s_add_u32 s74, s14, 0xffff0080
	s_addc_u32 s75, s15, -1
	s_mov_b32 s76, m0
	s_mov_b32 m0, s63
	s_nop 0
	global_load_lds_dwordx4 v156, s[74:75]
	s_mov_b32 m0, s76
	ds_read_b64_tr_b16 v[152:153], v203 offset:36864
	ds_read_b64_tr_b16 v[154:155], v203 offset:38912
	v_mfma_f32_16x16x32_bf16 v[66:69], v[6:9], v[26:29], v[66:69]
	v_exp_f32_e32 v116, v116
	s_waitcnt lgkmcnt(14)
	v_mfma_f32_16x16x32_bf16 v[62:65], v[6:9], v[162:165], v[62:65]
	v_mfma_f32_16x16x32_bf16 v[70:73], v[2:5], v[26:29], v[70:73]
	v_exp_f32_e32 v117, v117
	v_mfma_f32_16x16x32_bf16 v[78:81], v[2:5], v[162:165], v[78:81]
	ds_read_b64_tr_b16 v[158:159], v204 offset:36864
	ds_read_b64_tr_b16 v[160:161], v204 offset:38912
	v_mfma_f32_16x16x32_bf16 v[74:77], v[6:9], v[166:169], v[74:77]
	v_exp_f32_e32 v118, v118
	v_mfma_f32_16x16x32_bf16 v[82:85], v[2:5], v[166:169], v[82:85]
	v_exp_f32_e32 v119, v119
	ds_read_b64_tr_b16 v[162:163], v205 offset:36864
	ds_read_b64_tr_b16 v[164:165], v205 offset:38912
	s_waitcnt lgkmcnt(14)
	v_mfma_f32_16x16x32_bf16 v[90:93], v[6:9], v[144:147], v[90:93]
	v_exp_f32_e32 v58, v58
	v_mfma_f32_16x16x32_bf16 v[94:97], v[2:5], v[144:147], v[94:97]
	v_exp_f32_e32 v59, v59
	ds_read_b64_tr_b16 v[144:145], v206 offset:36864
	ds_read_b64_tr_b16 v[146:147], v206 offset:38912
	v_mfma_f32_16x16x32_bf16 v[98:101], v[6:9], v[170:173], v[98:101]
	v_exp_f32_e32 v60, v60
	v_mfma_f32_16x16x32_bf16 v[102:105], v[2:5], v[170:173], v[102:105]
	v_exp_f32_e32 v61, v61
	ds_read_b64_tr_b16 v[166:167], v203 offset:45056
	ds_read_b64_tr_b16 v[168:169], v203 offset:47104
	s_waitcnt lgkmcnt(14)
	v_mfma_f32_16x16x32_bf16 v[136:139], v[6:9], v[174:177], v[136:139]
	v_exp_f32_e32 v86, v86
	s_nop 0
	v_exp_f32_e32 v87, v87
	v_mfma_f32_16x16x32_bf16 v[140:143], v[2:5], v[174:177], v[140:143]
	ds_read_b64_tr_b16 v[170:171], v204 offset:45056
	ds_read_b64_tr_b16 v[172:173], v204 offset:47104
	v_exp_f32_e32 v88, v88
	v_mfma_f32_16x16x32_bf16 v[174:177], v[6:9], v[208:211], v[128:131]
	v_mfma_f32_16x16x32_bf16 v[132:135], v[2:5], v[208:211], v[132:135]
	v_exp_f32_e32 v89, v89
	ds_read_b64_tr_b16 v[208:209], v205 offset:45056
	ds_read_b64_tr_b16 v[210:211], v205 offset:47104
	v_exp_f32_e32 v54, v54
	s_waitcnt lgkmcnt(14)
	v_mfma_f32_16x16x32_bf16 v[216:219], v[6:9], v[148:151], v[120:123]
	s_nop 0
	v_exp_f32_e32 v55, v55
	v_mfma_f32_16x16x32_bf16 v[148:151], v[2:5], v[148:151], v[124:127]
	ds_read_b64_tr_b16 v[220:221], v206 offset:45056
	ds_read_b64_tr_b16 v[222:223], v206 offset:47104
	v_exp_f32_e32 v56, v56
	v_mfma_f32_16x16x32_bf16 v[224:227], v[6:9], v[212:215], v[106:109]
	s_nop 0
	v_exp_f32_e32 v57, v57
	v_mfma_f32_16x16x32_bf16 v[212:215], v[2:5], v[212:215], v[110:113]
	ds_read_b128 v[128:131], v1
	v_mfma_f32_16x16x32_bf16 v[66:69], v[34:37], v[26:29], v[66:69]
	v_exp_f32_e32 v38, v38
	v_cvt_pk_bf16_f32 v6, v116, v117
	s_waitcnt lgkmcnt(14)
	v_mfma_f32_16x16x32_bf16 v[62:65], v[34:37], v[152:155], v[62:65]
	v_mfma_f32_16x16x32_bf16 v[70:73], v[30:33], v[26:29], v[70:73]
	v_exp_f32_e32 v39, v39
	v_cvt_pk_bf16_f32 v7, v118, v119
	v_mfma_f32_16x16x32_bf16 v[78:81], v[30:33], v[152:155], v[78:81]
	ds_read_b128 v[152:155], v115
	s_waitcnt lgkmcnt(14)
; #define ATT_WAIT_BARV(N) asm volatile("s_waitcnt vmcnt(" #N ")\n\ts_barrier" ::: "memory")
; __device__ __forceinline__ void attn_unit_d16(const UnitDesc& U, char* shm, float lam, const float* subw) {
;     ...
;         STEP_D16(t + 2, true, true, true, 3, 0, 2, 2, 1); ATT_WAIT_BARV(4);
;         STEP_D16(t + 3, true, true, true, 0, 1, 3, 3, 2); ATT_WAIT_BARV(4);
	v_mfma_f32_16x16x32_bf16 v[74:77], v[34:37], v[158:161], v[74:77]
	v_exp_f32_e32 v40, v40
	v_cvt_pk_bf16_f32 v8, v86, v87
	v_mfma_f32_16x16x32_bf16 v[82:85], v[30:33], v[158:161], v[82:85]
	v_exp_f32_e32 v41, v41
	v_cvt_pk_bf16_f32 v9, v88, v89
	ds_read_b128 v[158:161], v1 offset:2048
	s_waitcnt lgkmcnt(13)
	v_mfma_f32_16x16x32_bf16 v[86:89], v[34:37], v[162:165], v[90:93]
	v_exp_f32_e32 v42, v42
	v_cvt_pk_bf16_f32 v2, v58, v59
	v_mfma_f32_16x16x32_bf16 v[90:93], v[30:33], v[162:165], v[94:97]
	v_exp_f32_e32 v43, v43
	v_cvt_pk_bf16_f32 v3, v60, v61
	ds_read_b128 v[162:165], v115 offset:2048
	s_waitcnt lgkmcnt(12)
	v_mfma_f32_16x16x32_bf16 v[58:61], v[34:37], v[144:147], v[98:101]
	v_exp_f32_e32 v44, v44
	v_cvt_pk_bf16_f32 v4, v54, v55
	v_mfma_f32_16x16x32_bf16 v[94:97], v[30:33], v[144:147], v[102:105]
	v_exp_f32_e32 v45, v45
	v_cvt_pk_bf16_f32 v5, v56, v57
	ds_read_b128 v[144:147], v1 offset:4096
	s_waitcnt lgkmcnt(11)
	v_mfma_f32_16x16x32_bf16 v[120:123], v[34:37], v[166:169], v[136:139]
	v_exp_f32_e32 v46, v46
	v_mfma_f32_16x16x32_bf16 v[124:127], v[30:33], v[166:169], v[140:143]
	v_exp_f32_e32 v47, v47
	ds_read_b128 v[136:139], v115 offset:4096
	s_waitcnt lgkmcnt(10)
	v_mfma_f32_16x16x32_bf16 v[110:113], v[34:37], v[170:173], v[174:177]
	v_exp_f32_e32 v48, v48
	v_mfma_f32_16x16x32_bf16 v[116:119], v[30:33], v[170:173], v[132:135]
	v_exp_f32_e32 v49, v49
	s_nop 1
	ds_read_b128 v[132:135], v1 offset:6144
	s_waitcnt lgkmcnt(9)
	v_mfma_f32_16x16x32_bf16 v[102:105], v[34:37], v[208:211], v[216:219]
	v_exp_f32_e32 v50, v50
	v_mfma_f32_16x16x32_bf16 v[106:109], v[30:33], v[208:211], v[148:151]
	v_exp_f32_e32 v51, v51
	ds_read_b128 v[166:169], v115 offset:6144
	s_waitcnt lgkmcnt(8)
	v_mfma_f32_16x16x32_bf16 v[54:57], v[34:37], v[220:223], v[224:227]
	v_exp_f32_e32 v52, v52
	v_mfma_f32_16x16x32_bf16 v[98:101], v[30:33], v[220:223], v[212:215]
	v_exp_f32_e32 v53, v53
	v_cvt_pk_bf16_f32 v34, v38, v39
	v_cvt_pk_bf16_f32 v35, v40, v41
	v_cvt_pk_bf16_f32 v36, v46, v47
	v_cvt_pk_bf16_f32 v37, v48, v49
	v_cvt_pk_bf16_f32 v30, v42, v43
	v_cvt_pk_bf16_f32 v31, v44, v45
	v_cvt_pk_bf16_f32 v32, v50, v51
	v_cvt_pk_bf16_f32 v33, v52, v53
	s_waitcnt vmcnt(8)
	s_barrier
	ds_read_b64_tr_b16 v[170:171], v203 offset:49152
	ds_read_b64_tr_b16 v[172:173], v203 offset:51200
	s_waitcnt lgkmcnt(9)
	v_mfma_f32_16x16x32_bf16 v[38:41], v[128:131], v[10:13], 0
	s_waitcnt lgkmcnt(8)
	v_mfma_f32_16x16x32_bf16 v[50:53], v[152:155], v[14:17], v[38:41]
	ds_read_b64_tr_b16 v[174:175], v204 offset:49152
	ds_read_b64_tr_b16 v[176:177], v204 offset:51200
	v_mfma_f32_16x16x32_bf16 v[38:41], v[128:131], v[18:21], 0
	v_mfma_f32_16x16x32_bf16 v[42:45], v[152:155], v[22:25], v[38:41]
	ds_read_b64_tr_b16 v[128:129], v205 offset:49152
	ds_read_b64_tr_b16 v[130:131], v205 offset:51200
	s_waitcnt lgkmcnt(11)
	v_mfma_f32_16x16x32_bf16 v[38:41], v[158:161], v[10:13], 0
	s_waitcnt lgkmcnt(10)
	v_mfma_f32_16x16x32_bf16 v[46:49], v[162:165], v[14:17], v[38:41]
	ds_read_b64_tr_b16 v[208:209], v206 offset:49152
	ds_read_b64_tr_b16 v[210:211], v206 offset:51200
	v_mfma_f32_16x16x32_bf16 v[38:41], v[158:161], v[18:21], 0
	v_mfma_f32_16x16x32_bf16 v[38:41], v[162:165], v[22:25], v[38:41]
	ds_read_b64_tr_b16 v[158:159], v203 offset:57344
	ds_read_b64_tr_b16 v[160:161], v203 offset:59392
	s_waitcnt lgkmcnt(13)
	v_mfma_f32_16x16x32_bf16 v[140:143], v[144:147], v[10:13], 0
	s_waitcnt lgkmcnt(12)
	v_mfma_f32_16x16x32_bf16 v[140:143], v[136:139], v[14:17], v[140:143]
	ds_read_b64_tr_b16 v[162:163], v204 offset:57344
	ds_read_b64_tr_b16 v[164:165], v204 offset:59392
	v_mfma_f32_16x16x32_bf16 v[144:147], v[144:147], v[18:21], 0
	v_mfma_f32_16x16x32_bf16 v[144:147], v[136:139], v[22:25], v[144:147]
	ds_read_b64_tr_b16 v[136:137], v205 offset:57344
	ds_read_b64_tr_b16 v[138:139], v205 offset:59392
	s_waitcnt lgkmcnt(14)
	v_mfma_f32_16x16x32_bf16 v[148:151], v[132:135], v[10:13], 0
	v_mfma_f32_16x16x32_bf16 v[148:151], v[166:169], v[14:17], v[148:151]
	ds_read_b64_tr_b16 v[212:213], v206 offset:57344
	ds_read_b64_tr_b16 v[214:215], v206 offset:59392
	v_mfma_f32_16x16x32_bf16 v[132:135], v[132:135], v[18:21], 0
	v_mfma_f32_16x16x32_bf16 v[152:155], v[166:169], v[22:25], v[132:135]
	s_add_u32 s74, s14, 0xfd020000
	s_addc_u32 s75, s15, -1
	s_mov_b32 s76, m0
	s_mov_b32 m0, s30
	s_nop 0
	global_load_lds_dwordx4 v157, s[74:75]
	s_mov_b32 m0, s76
	s_add_u32 s74, s14, 0xfd020080
	s_addc_u32 s75, s15, -1
	s_mov_b32 s76, m0
	s_mov_b32 m0, s31
	s_nop 0
	global_load_lds_dwordx4 v157, s[74:75]
	s_mov_b32 m0, s76
	s_mov_b32 s74, m0
	s_mov_b32 m0, s29
	s_nop 0
	global_load_lds_dwordx4 v156, s[14:15]
	s_mov_b32 m0, s74
	s_add_u32 s74, s14, 0x80
	s_addc_u32 s75, s15, 0
	s_mov_b32 s76, m0
	s_mov_b32 m0, s67
	s_nop 0
	global_load_lds_dwordx4 v156, s[74:75]
	s_mov_b32 m0, s76
	s_nop 0
	ds_read_b64_tr_b16 v[132:133], v203 offset:53248
	ds_read_b64_tr_b16 v[134:135], v203 offset:55296
	v_mfma_f32_16x16x32_bf16 v[66:69], v[6:9], v[26:29], v[66:69]
	v_exp_f32_e32 v50, v50
	s_waitcnt lgkmcnt(14)
	v_mfma_f32_16x16x32_bf16 v[62:65], v[6:9], v[170:173], v[62:65]
	v_mfma_f32_16x16x32_bf16 v[70:73], v[2:5], v[26:29], v[70:73]
	v_exp_f32_e32 v51, v51
	v_mfma_f32_16x16x32_bf16 v[78:81], v[2:5], v[170:173], v[78:81]
	ds_read_b64_tr_b16 v[166:167], v204 offset:53248
	ds_read_b64_tr_b16 v[168:169], v204 offset:55296
	v_mfma_f32_16x16x32_bf16 v[74:77], v[6:9], v[174:177], v[74:77]
	v_exp_f32_e32 v52, v52
	v_mfma_f32_16x16x32_bf16 v[82:85], v[2:5], v[174:177], v[82:85]
	v_exp_f32_e32 v53, v53
	ds_read_b64_tr_b16 v[170:171], v205 offset:53248
	ds_read_b64_tr_b16 v[172:173], v205 offset:55296
	s_waitcnt lgkmcnt(14)
; #define ATT_WAIT_BARV(N) asm volatile("s_waitcnt vmcnt(" #N ")\n\ts_barrier" ::: "memory")
; __device__ __forceinline__ void attn_unit_d16(const UnitDesc& U, char* shm, float lam, const float* subw) {
;     ...
;     for (int t = 1; t <= NT - 4; t += 4) {
;         STEP_D16(t, true, true, true, 1, 2, 0, 0, 3);     ATT_WAIT_BARV(4);
;         STEP_D16(t + 1, true, true, true, 2, 3, 1, 1, 0); ATT_WAIT_BARV(4);
;         STEP_D16(t + 2, true, true, true, 3, 0, 2, 2, 1); ATT_WAIT_BARV(4);
;         STEP_D16(t + 3, true, true, true, 0, 1, 3, 3, 2); ATT_WAIT_BARV(4);
;     }
	v_mfma_f32_16x16x32_bf16 v[86:89], v[6:9], v[128:131], v[86:89]
	v_exp_f32_e32 v42, v42
	v_mfma_f32_16x16x32_bf16 v[128:131], v[2:5], v[128:131], v[90:93]
	v_exp_f32_e32 v43, v43
	ds_read_b64_tr_b16 v[174:175], v206 offset:53248
	ds_read_b64_tr_b16 v[176:177], v206 offset:55296
	v_mfma_f32_16x16x32_bf16 v[58:61], v[6:9], v[208:211], v[58:61]
	v_exp_f32_e32 v44, v44
	s_nop 0
	v_exp_f32_e32 v45, v45
	v_mfma_f32_16x16x32_bf16 v[208:211], v[2:5], v[208:211], v[94:97]
	ds_read_b64_tr_b16 v[216:217], v203 offset:61440
	ds_read_b64_tr_b16 v[218:219], v203 offset:63488
	v_exp_f32_e32 v46, v46
	s_waitcnt lgkmcnt(14)
	v_mfma_f32_16x16x32_bf16 v[220:223], v[6:9], v[158:161], v[120:123]
	s_nop 0
	v_exp_f32_e32 v47, v47
	v_mfma_f32_16x16x32_bf16 v[158:161], v[2:5], v[158:161], v[124:127]
	ds_read_b64_tr_b16 v[224:225], v204 offset:61440
	ds_read_b64_tr_b16 v[226:227], v204 offset:63488
	v_exp_f32_e32 v48, v48
	v_mfma_f32_16x16x32_bf16 v[228:231], v[6:9], v[162:165], v[110:113]
	s_nop 0
	v_exp_f32_e32 v49, v49
	v_mfma_f32_16x16x32_bf16 v[162:165], v[2:5], v[162:165], v[116:119]
	ds_read_b64_tr_b16 v[232:233], v205 offset:61440
	ds_read_b64_tr_b16 v[234:235], v205 offset:63488
	v_exp_f32_e32 v38, v38
	s_waitcnt lgkmcnt(14)
	v_mfma_f32_16x16x32_bf16 v[236:239], v[6:9], v[136:139], v[102:105]
	v_mfma_f32_16x16x32_bf16 v[136:139], v[2:5], v[136:139], v[106:109]
	v_exp_f32_e32 v39, v39
	ds_read_b64_tr_b16 v[240:241], v206 offset:61440
	ds_read_b64_tr_b16 v[242:243], v206 offset:63488
	v_exp_f32_e32 v40, v40
	v_mfma_f32_16x16x32_bf16 v[244:247], v[6:9], v[212:215], v[54:57]
	s_nop 0
	v_exp_f32_e32 v41, v41
	v_mfma_f32_16x16x32_bf16 v[212:215], v[2:5], v[212:215], v[98:101]
	ds_read_b128 v[110:113], v1 offset:16384
	v_mfma_f32_16x16x32_bf16 v[106:109], v[34:37], v[26:29], v[66:69]
	v_exp_f32_e32 v140, v140
	v_cvt_pk_bf16_f32 v6, v50, v51
	s_waitcnt lgkmcnt(14)
	v_mfma_f32_16x16x32_bf16 v[98:101], v[34:37], v[132:135], v[62:65]
	v_mfma_f32_16x16x32_bf16 v[102:105], v[30:33], v[26:29], v[70:73]
	v_exp_f32_e32 v141, v141
	v_cvt_pk_bf16_f32 v7, v52, v53
	v_mfma_f32_16x16x32_bf16 v[90:93], v[30:33], v[132:135], v[78:81]
	ds_read_b128 v[26:29], v115 offset:16384
	s_waitcnt lgkmcnt(14)
	v_mfma_f32_16x16x32_bf16 v[94:97], v[34:37], v[166:169], v[74:77]
	v_exp_f32_e32 v142, v142
	v_cvt_pk_bf16_f32 v8, v46, v47
	v_mfma_f32_16x16x32_bf16 v[82:85], v[30:33], v[166:169], v[82:85]
	v_exp_f32_e32 v143, v143
	v_cvt_pk_bf16_f32 v9, v48, v49
	ds_read_b128 v[116:119], v1 offset:18432
	s_waitcnt lgkmcnt(13)
	v_mfma_f32_16x16x32_bf16 v[86:89], v[34:37], v[170:173], v[86:89]
	v_exp_f32_e32 v144, v144
	v_cvt_pk_bf16_f32 v2, v42, v43
	v_mfma_f32_16x16x32_bf16 v[74:77], v[30:33], v[170:173], v[128:131]
	v_exp_f32_e32 v145, v145
	v_cvt_pk_bf16_f32 v3, v44, v45
	ds_read_b128 v[120:123], v115 offset:18432
	s_waitcnt lgkmcnt(12)
	v_mfma_f32_16x16x32_bf16 v[78:81], v[34:37], v[174:177], v[58:61]
	v_exp_f32_e32 v146, v146
	v_cvt_pk_bf16_f32 v4, v38, v39
	v_mfma_f32_16x16x32_bf16 v[66:69], v[30:33], v[174:177], v[208:211]
	v_exp_f32_e32 v147, v147
	v_cvt_pk_bf16_f32 v5, v40, v41
	ds_read_b128 v[124:127], v1 offset:20480
	s_waitcnt lgkmcnt(11)
	v_mfma_f32_16x16x32_bf16 v[70:73], v[34:37], v[216:219], v[220:223]
	v_exp_f32_e32 v148, v148
	v_mfma_f32_16x16x32_bf16 v[58:61], v[30:33], v[216:219], v[158:161]
	v_exp_f32_e32 v149, v149
	ds_read_b128 v[132:135], v115 offset:20480
	s_waitcnt lgkmcnt(10)
	v_mfma_f32_16x16x32_bf16 v[62:65], v[34:37], v[224:227], v[228:231]
	v_exp_f32_e32 v150, v150
	v_mfma_f32_16x16x32_bf16 v[50:53], v[30:33], v[224:227], v[162:165]
	v_exp_f32_e32 v151, v151
	ds_read_b128 v[128:131], v1 offset:22528
	s_waitcnt lgkmcnt(9)
	v_mfma_f32_16x16x32_bf16 v[54:57], v[34:37], v[232:235], v[236:239]
	v_exp_f32_e32 v152, v152
	v_mfma_f32_16x16x32_bf16 v[42:45], v[30:33], v[232:235], v[136:139]
	v_exp_f32_e32 v153, v153
	s_nop 1
	ds_read_b128 v[136:139], v115 offset:22528
	s_waitcnt lgkmcnt(8)
	v_mfma_f32_16x16x32_bf16 v[46:49], v[34:37], v[240:243], v[244:247]
	v_exp_f32_e32 v154, v154
	v_mfma_f32_16x16x32_bf16 v[38:41], v[30:33], v[240:243], v[212:215]
	v_exp_f32_e32 v155, v155
	v_cvt_pk_bf16_f32 v34, v140, v141
	v_cvt_pk_bf16_f32 v35, v142, v143
	v_cvt_pk_bf16_f32 v36, v148, v149
	v_cvt_pk_bf16_f32 v37, v150, v151
	v_cvt_pk_bf16_f32 v30, v144, v145
	v_cvt_pk_bf16_f32 v31, v146, v147
	v_cvt_pk_bf16_f32 v32, v152, v153
	v_cvt_pk_bf16_f32 v33, v154, v155
	s_add_i32 s33, s33, 4
	s_add_u32 s14, s14, 0x40000
	s_waitcnt vmcnt(8)
	s_barrier
	s_addc_u32 s15, s15, 0
	s_cmpk_gt_u32 s33, 0x78
	s_cbranch_scc0 .LBB0_444
; #define ATT_WAIT_BAR(N) asm volatile("s_waitcnt vmcnt(" #N ") lgkmcnt(0)\n\ts_barrier" ::: "memory")
; __device__ __forceinline__ void attn_unit_d16(const UnitDesc& U, char* shm, float lam, const float* subw) {
;     ...
;     STEP_D16(NT - 3, false, true, true, 1, 2, 0, 0, 3);   ATT_WAIT_BAR(2);
	ds_read_b64_tr_b16 v[158:159], v203
	ds_read_b64_tr_b16 v[160:161], v203 offset:2048
	s_waitcnt lgkmcnt(9)
	v_mfma_f32_16x16x32_bf16 v[140:143], v[110:113], v[10:13], 0
	s_waitcnt lgkmcnt(8)
	v_mfma_f32_16x16x32_bf16 v[152:155], v[26:29], v[14:17], v[140:143]
	ds_read_b64_tr_b16 v[162:163], v204
	ds_read_b64_tr_b16 v[164:165], v204 offset:2048
	v_mfma_f32_16x16x32_bf16 v[110:113], v[110:113], v[18:21], 0
	v_mfma_f32_16x16x32_bf16 v[144:147], v[26:29], v[22:25], v[110:113]
	ds_read_b64_tr_b16 v[166:167], v205
	ds_read_b64_tr_b16 v[168:169], v205 offset:2048
	s_waitcnt lgkmcnt(11)
	v_mfma_f32_16x16x32_bf16 v[26:29], v[116:119], v[10:13], 0
	s_waitcnt lgkmcnt(10)
	v_mfma_f32_16x16x32_bf16 v[148:151], v[120:123], v[14:17], v[26:29]
	ds_read_b64_tr_b16 v[170:171], v206
	ds_read_b64_tr_b16 v[172:173], v206 offset:2048
	v_mfma_f32_16x16x32_bf16 v[26:29], v[116:119], v[18:21], 0
	v_mfma_f32_16x16x32_bf16 v[140:143], v[120:123], v[22:25], v[26:29]
	ds_read_b64_tr_b16 v[174:175], v203 offset:8192
	ds_read_b64_tr_b16 v[176:177], v203 offset:10240
	s_waitcnt lgkmcnt(13)
	v_mfma_f32_16x16x32_bf16 v[26:29], v[124:127], v[10:13], 0
	s_waitcnt lgkmcnt(12)
	v_mfma_f32_16x16x32_bf16 v[110:113], v[132:135], v[14:17], v[26:29]
	ds_read_b64_tr_b16 v[208:209], v204 offset:8192
	ds_read_b64_tr_b16 v[210:211], v204 offset:10240
	v_mfma_f32_16x16x32_bf16 v[26:29], v[124:127], v[18:21], 0
	v_mfma_f32_16x16x32_bf16 v[116:119], v[132:135], v[22:25], v[26:29]
	ds_read_b64_tr_b16 v[132:133], v205 offset:8192
	ds_read_b64_tr_b16 v[134:135], v205 offset:10240
	s_waitcnt lgkmcnt(14)
	v_mfma_f32_16x16x32_bf16 v[26:29], v[128:131], v[10:13], 0
	v_mfma_f32_16x16x32_bf16 v[120:123], v[136:139], v[14:17], v[26:29]
	ds_read_b64_tr_b16 v[212:213], v206 offset:8192
	ds_read_b64_tr_b16 v[214:215], v206 offset:10240
	v_mfma_f32_16x16x32_bf16 v[26:29], v[128:131], v[18:21], 0
	v_mfma_f32_16x16x32_bf16 v[124:127], v[136:139], v[22:25], v[26:29]
	s_add_u32 s14, s10, 0x7f0000
	s_addc_u32 s15, s11, 0
	s_mov_b32 s28, m0
	s_mov_b32 m0, s68
	s_nop 0
	global_load_lds_dwordx4 v156, s[14:15]
	s_mov_b32 m0, s28
	s_add_u32 s10, s10, 0x7f0080
	s_addc_u32 s11, s11, 0
	s_mov_b32 s14, m0
	s_mov_b32 m0, s69
	s_nop 0
	global_load_lds_dwordx4 v156, s[10:11]
	s_mov_b32 m0, s14
	ds_read_b64_tr_b16 v[128:129], v203 offset:4096
	ds_read_b64_tr_b16 v[130:131], v203 offset:6144
	s_nop 0
	v_mov_b64_e32 v[28:29], s[6:7]
	v_mov_b64_e32 v[26:27], s[4:5]
	v_exp_f32_e32 v152, v152
	s_waitcnt lgkmcnt(14)
	v_mfma_f32_16x16x32_bf16 v[98:101], v[6:9], v[158:161], v[98:101]
	v_mfma_f32_16x16x32_bf16 v[106:109], v[6:9], v[26:29], v[106:109]
	v_exp_f32_e32 v153, v153
	v_mfma_f32_16x16x32_bf16 v[102:105], v[2:5], v[26:29], v[102:105]
	v_mfma_f32_16x16x32_bf16 v[90:93], v[2:5], v[158:161], v[90:93]
	ds_read_b64_tr_b16 v[136:137], v204 offset:4096
	ds_read_b64_tr_b16 v[138:139], v204 offset:6144
	v_exp_f32_e32 v154, v154
	v_mfma_f32_16x16x32_bf16 v[94:97], v[6:9], v[162:165], v[94:97]
	v_mfma_f32_16x16x32_bf16 v[82:85], v[2:5], v[162:165], v[82:85]
	v_exp_f32_e32 v155, v155
	ds_read_b64_tr_b16 v[156:157], v205 offset:4096
	ds_read_b64_tr_b16 v[158:159], v205 offset:6144
	v_exp_f32_e32 v144, v144
	s_waitcnt lgkmcnt(14)
	v_mfma_f32_16x16x32_bf16 v[86:89], v[6:9], v[166:169], v[86:89]
	s_nop 0
	v_exp_f32_e32 v145, v145
	v_mfma_f32_16x16x32_bf16 v[160:163], v[2:5], v[166:169], v[74:77]
	ds_read_b64_tr_b16 v[164:165], v206 offset:4096
	ds_read_b64_tr_b16 v[166:167], v206 offset:6144
	v_exp_f32_e32 v146, v146
	v_mfma_f32_16x16x32_bf16 v[216:219], v[6:9], v[170:173], v[78:81]
	s_nop 0
	v_exp_f32_e32 v147, v147
	v_mfma_f32_16x16x32_bf16 v[168:171], v[2:5], v[170:173], v[66:69]
	ds_read_b64_tr_b16 v[220:221], v203 offset:12288
	ds_read_b64_tr_b16 v[222:223], v203 offset:14336
	v_exp_f32_e32 v148, v148
	s_waitcnt lgkmcnt(14)
	v_mfma_f32_16x16x32_bf16 v[224:227], v[6:9], v[174:177], v[70:73]
	v_mfma_f32_16x16x32_bf16 v[58:61], v[2:5], v[174:177], v[58:61]
	v_exp_f32_e32 v149, v149
	ds_read_b64_tr_b16 v[172:173], v204 offset:12288
	ds_read_b64_tr_b16 v[174:175], v204 offset:14336
	v_exp_f32_e32 v150, v150
	v_mfma_f32_16x16x32_bf16 v[176:179], v[6:9], v[208:211], v[62:65]
	v_mfma_f32_16x16x32_bf16 v[50:53], v[2:5], v[208:211], v[50:53]
	v_exp_f32_e32 v151, v151
	ds_read_b64_tr_b16 v[208:209], v205 offset:12288
	ds_read_b64_tr_b16 v[210:211], v205 offset:14336
	s_waitcnt lgkmcnt(14)
	v_mfma_f32_16x16x32_bf16 v[54:57], v[6:9], v[132:135], v[54:57]
	v_exp_f32_e32 v140, v140
	v_mfma_f32_16x16x32_bf16 v[42:45], v[2:5], v[132:135], v[42:45]
	v_exp_f32_e32 v141, v141
	ds_read_b64_tr_b16 v[228:229], v206 offset:12288
	ds_read_b64_tr_b16 v[230:231], v206 offset:14336
	v_mfma_f32_16x16x32_bf16 v[46:49], v[6:9], v[212:215], v[46:49]
	v_exp_f32_e32 v142, v142
	s_nop 0
	v_exp_f32_e32 v143, v143
	v_mfma_f32_16x16x32_bf16 v[212:215], v[2:5], v[212:215], v[38:41]
	s_nop 2
	ds_read_b128 v[38:41], v1 offset:32768
	v_mfma_f32_16x16x32_bf16 v[66:69], v[34:37], v[26:29], v[106:109]
	v_exp_f32_e32 v110, v110
	v_cvt_pk_bf16_f32 v6, v152, v153
	s_waitcnt lgkmcnt(14)
	v_mfma_f32_16x16x32_bf16 v[62:65], v[34:37], v[128:131], v[98:101]
	v_mfma_f32_16x16x32_bf16 v[70:73], v[30:33], v[26:29], v[102:105]
	v_exp_f32_e32 v111, v111
	v_cvt_pk_bf16_f32 v7, v154, v155
	v_mfma_f32_16x16x32_bf16 v[78:81], v[30:33], v[128:131], v[90:93]
	ds_read_b128 v[232:235], v115 offset:32768
	s_waitcnt lgkmcnt(14)
	v_mfma_f32_16x16x32_bf16 v[74:77], v[34:37], v[136:139], v[94:97]
	v_exp_f32_e32 v112, v112
	v_cvt_pk_bf16_f32 v8, v148, v149
	v_mfma_f32_16x16x32_bf16 v[82:85], v[30:33], v[136:139], v[82:85]
	v_exp_f32_e32 v113, v113
	v_cvt_pk_bf16_f32 v9, v150, v151
	ds_read_b128 v[236:239], v1 offset:34816
	v_exp_f32_e32 v116, v116
	v_cvt_pk_bf16_f32 v2, v144, v145
	s_waitcnt lgkmcnt(13)
; #define ATT_WAIT_BAR(N) asm volatile("s_waitcnt vmcnt(" #N ") lgkmcnt(0)\n\ts_barrier" ::: "memory")
; __device__ __forceinline__ void attn_unit_d16(const UnitDesc& U, char* shm, float lam, const float* subw) {
;     ...
;     STEP_D16(NT - 3, false, true, true, 1, 2, 0, 0, 3);   ATT_WAIT_BAR(2);
;     STEP_D16(NT - 2, false, false, true, 2, 3, 1, 1, 0);  ATT_WAIT_BAR(0);
	v_mfma_f32_16x16x32_bf16 v[90:93], v[34:37], v[156:159], v[86:89]
	s_nop 0
	v_exp_f32_e32 v117, v117
	v_cvt_pk_bf16_f32 v3, v146, v147
	v_mfma_f32_16x16x32_bf16 v[94:97], v[30:33], v[156:159], v[160:163]
	ds_read_b128 v[156:159], v115 offset:34816
	v_exp_f32_e32 v118, v118
	v_cvt_pk_bf16_f32 v4, v140, v141
	s_waitcnt lgkmcnt(12)
	v_mfma_f32_16x16x32_bf16 v[98:101], v[34:37], v[164:167], v[216:219]
	s_nop 0
	v_exp_f32_e32 v119, v119
	v_cvt_pk_bf16_f32 v5, v142, v143
	v_mfma_f32_16x16x32_bf16 v[102:105], v[30:33], v[164:167], v[168:171]
	ds_read_b128 v[160:163], v1 offset:36864
	v_exp_f32_e32 v120, v120
	s_waitcnt lgkmcnt(11)
	v_mfma_f32_16x16x32_bf16 v[148:151], v[34:37], v[220:223], v[224:227]
	s_nop 0
	v_exp_f32_e32 v121, v121
	v_mfma_f32_16x16x32_bf16 v[152:155], v[30:33], v[220:223], v[58:61]
	ds_read_b128 v[164:167], v115 offset:36864
	v_exp_f32_e32 v122, v122
	s_waitcnt lgkmcnt(10)
	v_mfma_f32_16x16x32_bf16 v[140:143], v[34:37], v[172:175], v[176:179]
	s_nop 0
	v_exp_f32_e32 v123, v123
	v_mfma_f32_16x16x32_bf16 v[144:147], v[30:33], v[172:175], v[50:53]
	s_nop 2
	ds_read_b128 v[50:53], v1 offset:38912
	v_exp_f32_e32 v124, v124
	s_waitcnt lgkmcnt(9)
	v_mfma_f32_16x16x32_bf16 v[132:135], v[34:37], v[208:211], v[54:57]
	s_nop 0
	v_exp_f32_e32 v125, v125
	v_mfma_f32_16x16x32_bf16 v[136:139], v[30:33], v[208:211], v[42:45]
	ds_read_b128 v[168:171], v115 offset:38912
	v_exp_f32_e32 v126, v126
	s_waitcnt lgkmcnt(8)
	v_mfma_f32_16x16x32_bf16 v[106:109], v[34:37], v[228:231], v[46:49]
	s_nop 0
	v_exp_f32_e32 v127, v127
	v_mfma_f32_16x16x32_bf16 v[128:131], v[30:33], v[228:231], v[212:215]
	v_cvt_pk_bf16_f32 v34, v110, v111
	v_cvt_pk_bf16_f32 v35, v112, v113
	v_cvt_pk_bf16_f32 v36, v120, v121
	v_cvt_pk_bf16_f32 v37, v122, v123
	v_cvt_pk_bf16_f32 v30, v116, v117
	v_cvt_pk_bf16_f32 v31, v118, v119
	v_cvt_pk_bf16_f32 v32, v124, v125
	v_cvt_pk_bf16_f32 v33, v126, v127
	s_waitcnt vmcnt(2) lgkmcnt(0)
	s_barrier
	ds_read_b64_tr_b16 v[116:117], v203 offset:16384
	ds_read_b64_tr_b16 v[118:119], v203 offset:18432
	s_waitcnt lgkmcnt(9)
	v_mfma_f32_16x16x32_bf16 v[42:45], v[38:41], v[10:13], 0
	s_waitcnt lgkmcnt(8)
	v_mfma_f32_16x16x32_bf16 v[110:113], v[232:235], v[14:17], v[42:45]
	ds_read_b64_tr_b16 v[120:121], v204 offset:16384
	ds_read_b64_tr_b16 v[122:123], v204 offset:18432
	v_mfma_f32_16x16x32_bf16 v[38:41], v[38:41], v[18:21], 0
	v_mfma_f32_16x16x32_bf16 v[58:61], v[232:235], v[22:25], v[38:41]
	ds_read_b64_tr_b16 v[124:125], v205 offset:16384
	ds_read_b64_tr_b16 v[126:127], v205 offset:18432
	s_waitcnt lgkmcnt(11)
	v_mfma_f32_16x16x32_bf16 v[38:41], v[236:239], v[10:13], 0
	s_waitcnt lgkmcnt(10)
	v_mfma_f32_16x16x32_bf16 v[86:89], v[156:159], v[14:17], v[38:41]
	ds_read_b64_tr_b16 v[172:173], v206 offset:16384
	ds_read_b64_tr_b16 v[174:175], v206 offset:18432
	v_mfma_f32_16x16x32_bf16 v[38:41], v[236:239], v[18:21], 0
	v_mfma_f32_16x16x32_bf16 v[54:57], v[156:159], v[22:25], v[38:41]
	ds_read_b64_tr_b16 v[156:157], v203 offset:24576
	ds_read_b64_tr_b16 v[158:159], v203 offset:26624
	s_waitcnt lgkmcnt(13)
	v_mfma_f32_16x16x32_bf16 v[38:41], v[160:163], v[10:13], 0
	s_waitcnt lgkmcnt(12)
	v_mfma_f32_16x16x32_bf16 v[38:41], v[164:167], v[14:17], v[38:41]
	ds_read_b64_tr_b16 v[176:177], v204 offset:24576
	ds_read_b64_tr_b16 v[178:179], v204 offset:26624
	v_mfma_f32_16x16x32_bf16 v[42:45], v[160:163], v[18:21], 0
	v_mfma_f32_16x16x32_bf16 v[42:45], v[164:167], v[22:25], v[42:45]
	ds_read_b64_tr_b16 v[160:161], v205 offset:24576
	ds_read_b64_tr_b16 v[162:163], v205 offset:26624
	s_waitcnt lgkmcnt(14)
	v_mfma_f32_16x16x32_bf16 v[46:49], v[50:53], v[10:13], 0
	v_mfma_f32_16x16x32_bf16 v[46:49], v[168:171], v[14:17], v[46:49]
	ds_read_b64_tr_b16 v[164:165], v206 offset:24576
	ds_read_b64_tr_b16 v[166:167], v206 offset:26624
	v_mfma_f32_16x16x32_bf16 v[50:53], v[50:53], v[18:21], 0
	v_mfma_f32_16x16x32_bf16 v[50:53], v[168:171], v[22:25], v[50:53]
	ds_read_b64_tr_b16 v[168:169], v203 offset:20480
	ds_read_b64_tr_b16 v[170:171], v203 offset:22528
	v_mfma_f32_16x16x32_bf16 v[66:69], v[6:9], v[26:29], v[66:69]
	v_exp_f32_e32 v110, v110
	s_waitcnt lgkmcnt(14)
	v_mfma_f32_16x16x32_bf16 v[62:65], v[6:9], v[116:119], v[62:65]
	v_mfma_f32_16x16x32_bf16 v[70:73], v[2:5], v[26:29], v[70:73]
	v_exp_f32_e32 v111, v111
	v_mfma_f32_16x16x32_bf16 v[78:81], v[2:5], v[116:119], v[78:81]
	ds_read_b64_tr_b16 v[116:117], v204 offset:20480
	ds_read_b64_tr_b16 v[118:119], v204 offset:22528
	v_mfma_f32_16x16x32_bf16 v[74:77], v[6:9], v[120:123], v[74:77]
	v_exp_f32_e32 v112, v112
	v_mfma_f32_16x16x32_bf16 v[82:85], v[2:5], v[120:123], v[82:85]
	v_exp_f32_e32 v113, v113
	ds_read_b64_tr_b16 v[120:121], v205 offset:20480
	ds_read_b64_tr_b16 v[122:123], v205 offset:22528
	v_exp_f32_e32 v58, v58
	s_waitcnt lgkmcnt(14)
	v_mfma_f32_16x16x32_bf16 v[90:93], v[6:9], v[124:127], v[90:93]
	s_nop 0
	v_exp_f32_e32 v59, v59
	v_mfma_f32_16x16x32_bf16 v[94:97], v[2:5], v[124:127], v[94:97]
	ds_read_b64_tr_b16 v[124:125], v206 offset:20480
	ds_read_b64_tr_b16 v[126:127], v206 offset:22528
	v_exp_f32_e32 v60, v60
	v_mfma_f32_16x16x32_bf16 v[98:101], v[6:9], v[172:175], v[98:101]
	s_nop 0
	v_exp_f32_e32 v61, v61
	v_mfma_f32_16x16x32_bf16 v[102:105], v[2:5], v[172:175], v[102:105]
	ds_read_b64_tr_b16 v[172:173], v203 offset:28672
	ds_read_b64_tr_b16 v[174:175], v203 offset:30720
	v_exp_f32_e32 v86, v86
	s_waitcnt lgkmcnt(14)
; #define ATT_WAIT_BAR(N) asm volatile("s_waitcnt vmcnt(" #N ") lgkmcnt(0)\n\ts_barrier" ::: "memory")
; __device__ __forceinline__ void attn_unit_d16(const UnitDesc& U, char* shm, float lam, const float* subw) {
;     ...
;     STEP_D16(NT - 2, false, false, true, 2, 3, 1, 1, 0);  ATT_WAIT_BAR(0);
;     STEP_D16(NT - 1, false, false, false, 3, 0, 2, 2, 1); ATT_WAIT_BAR(0);
	v_mfma_f32_16x16x32_bf16 v[148:151], v[6:9], v[156:159], v[148:151]
	s_nop 0
	v_exp_f32_e32 v87, v87
	v_mfma_f32_16x16x32_bf16 v[152:155], v[2:5], v[156:159], v[152:155]
	ds_read_b64_tr_b16 v[156:157], v204 offset:28672
	ds_read_b64_tr_b16 v[158:159], v204 offset:30720
	v_exp_f32_e32 v88, v88
	v_mfma_f32_16x16x32_bf16 v[140:143], v[6:9], v[176:179], v[140:143]
	s_nop 0
	v_exp_f32_e32 v89, v89
	v_mfma_f32_16x16x32_bf16 v[144:147], v[2:5], v[176:179], v[144:147]
	ds_read_b64_tr_b16 v[176:177], v205 offset:28672
	ds_read_b64_tr_b16 v[178:179], v205 offset:30720
	v_exp_f32_e32 v54, v54
	s_waitcnt lgkmcnt(14)
	v_mfma_f32_16x16x32_bf16 v[208:211], v[6:9], v[160:163], v[132:135]
	s_nop 0
	v_exp_f32_e32 v55, v55
	v_mfma_f32_16x16x32_bf16 v[160:163], v[2:5], v[160:163], v[136:139]
	ds_read_b64_tr_b16 v[212:213], v206 offset:28672
	ds_read_b64_tr_b16 v[214:215], v206 offset:30720
	v_exp_f32_e32 v56, v56
	v_mfma_f32_16x16x32_bf16 v[216:219], v[6:9], v[164:167], v[106:109]
	s_nop 0
	v_exp_f32_e32 v57, v57
	v_mfma_f32_16x16x32_bf16 v[164:167], v[2:5], v[164:167], v[128:131]
	ds_read_b128 v[136:139], v1 offset:49152
	v_mfma_f32_16x16x32_bf16 v[66:69], v[34:37], v[26:29], v[66:69]
	v_exp_f32_e32 v38, v38
	v_cvt_pk_bf16_f32 v6, v110, v111
	s_waitcnt lgkmcnt(14)
	v_mfma_f32_16x16x32_bf16 v[62:65], v[34:37], v[168:171], v[62:65]
	v_mfma_f32_16x16x32_bf16 v[70:73], v[30:33], v[26:29], v[70:73]
	v_exp_f32_e32 v39, v39
	v_cvt_pk_bf16_f32 v7, v112, v113
	v_mfma_f32_16x16x32_bf16 v[78:81], v[30:33], v[168:171], v[78:81]
	ds_read_b128 v[168:171], v115 offset:49152
	s_waitcnt lgkmcnt(14)
	v_mfma_f32_16x16x32_bf16 v[74:77], v[34:37], v[116:119], v[74:77]
	v_exp_f32_e32 v40, v40
	v_cvt_pk_bf16_f32 v8, v86, v87
	v_mfma_f32_16x16x32_bf16 v[82:85], v[30:33], v[116:119], v[82:85]
	v_exp_f32_e32 v41, v41
	v_cvt_pk_bf16_f32 v9, v88, v89
	ds_read_b128 v[220:223], v1 offset:51200
	v_exp_f32_e32 v42, v42
	v_cvt_pk_bf16_f32 v2, v58, v59
	s_waitcnt lgkmcnt(13)
	v_mfma_f32_16x16x32_bf16 v[86:89], v[34:37], v[120:123], v[90:93]
	s_nop 0
	v_exp_f32_e32 v43, v43
	v_cvt_pk_bf16_f32 v3, v60, v61
	v_mfma_f32_16x16x32_bf16 v[90:93], v[30:33], v[120:123], v[94:97]
	ds_read_b128 v[224:227], v115 offset:51200
	s_waitcnt lgkmcnt(12)
	v_mfma_f32_16x16x32_bf16 v[58:61], v[34:37], v[124:127], v[98:101]
	v_exp_f32_e32 v44, v44
	v_cvt_pk_bf16_f32 v4, v54, v55
	s_nop 0
	v_exp_f32_e32 v45, v45
	v_cvt_pk_bf16_f32 v5, v56, v57
	v_mfma_f32_16x16x32_bf16 v[94:97], v[30:33], v[124:127], v[102:105]
	ds_read_b128 v[228:231], v1 offset:53248
	v_exp_f32_e32 v46, v46
	s_waitcnt lgkmcnt(11)
	v_mfma_f32_16x16x32_bf16 v[128:131], v[34:37], v[172:175], v[148:151]
	s_nop 0
	v_exp_f32_e32 v47, v47
	v_mfma_f32_16x16x32_bf16 v[132:135], v[30:33], v[172:175], v[152:155]
	ds_read_b128 v[148:151], v115 offset:53248
	v_exp_f32_e32 v48, v48
	s_waitcnt lgkmcnt(10)
	v_mfma_f32_16x16x32_bf16 v[120:123], v[34:37], v[156:159], v[140:143]
	s_nop 0
	v_exp_f32_e32 v49, v49
	v_mfma_f32_16x16x32_bf16 v[124:127], v[30:33], v[156:159], v[144:147]
	ds_read_b128 v[140:143], v1 offset:55296
	v_exp_f32_e32 v50, v50
	s_waitcnt lgkmcnt(9)
	v_mfma_f32_16x16x32_bf16 v[106:109], v[34:37], v[176:179], v[208:211]
	s_nop 0
	v_exp_f32_e32 v51, v51
	v_mfma_f32_16x16x32_bf16 v[110:113], v[30:33], v[176:179], v[160:163]
	ds_read_b128 v[144:147], v115 offset:55296
	v_exp_f32_e32 v52, v52
	s_waitcnt lgkmcnt(8)
	v_mfma_f32_16x16x32_bf16 v[98:101], v[34:37], v[212:215], v[216:219]
	s_nop 0
	v_exp_f32_e32 v53, v53
	v_mfma_f32_16x16x32_bf16 v[102:105], v[30:33], v[212:215], v[164:167]
	v_cvt_pk_bf16_f32 v34, v38, v39
	v_cvt_pk_bf16_f32 v35, v40, v41
	v_cvt_pk_bf16_f32 v36, v46, v47
	v_cvt_pk_bf16_f32 v37, v48, v49
	v_cvt_pk_bf16_f32 v30, v42, v43
	v_cvt_pk_bf16_f32 v31, v44, v45
	v_cvt_pk_bf16_f32 v32, v50, v51
	v_cvt_pk_bf16_f32 v33, v52, v53
	s_waitcnt vmcnt(0) lgkmcnt(0)
	s_barrier
	ds_read_b64_tr_b16 v[152:153], v203 offset:32768
	ds_read_b64_tr_b16 v[154:155], v203 offset:34816
	s_waitcnt lgkmcnt(9)
	v_mfma_f32_16x16x32_bf16 v[38:41], v[136:139], v[10:13], 0
	s_waitcnt lgkmcnt(8)
	v_mfma_f32_16x16x32_bf16 v[116:119], v[168:171], v[14:17], v[38:41]
	ds_read_b64_tr_b16 v[156:157], v204 offset:32768
	ds_read_b64_tr_b16 v[158:159], v204 offset:34816
	v_mfma_f32_16x16x32_bf16 v[38:41], v[136:139], v[18:21], 0
	v_mfma_f32_16x16x32_bf16 v[50:53], v[168:171], v[22:25], v[38:41]
	ds_read_b64_tr_b16 v[136:137], v205 offset:32768
	ds_read_b64_tr_b16 v[138:139], v205 offset:34816
	s_waitcnt lgkmcnt(11)
	v_mfma_f32_16x16x32_bf16 v[38:41], v[220:223], v[10:13], 0
	s_waitcnt lgkmcnt(10)
	v_mfma_f32_16x16x32_bf16 v[54:57], v[224:227], v[14:17], v[38:41]
	ds_read_b64_tr_b16 v[160:161], v206 offset:32768
	ds_read_b64_tr_b16 v[162:163], v206 offset:34816
	v_mfma_f32_16x16x32_bf16 v[38:41], v[220:223], v[18:21], 0
	v_mfma_f32_16x16x32_bf16 v[46:49], v[224:227], v[22:25], v[38:41]
	ds_read_b64_tr_b16 v[164:165], v203 offset:40960
	ds_read_b64_tr_b16 v[166:167], v203 offset:43008
	s_waitcnt lgkmcnt(13)
	v_mfma_f32_16x16x32_bf16 v[38:41], v[228:231], v[10:13], 0
	s_waitcnt lgkmcnt(12)
	v_mfma_f32_16x16x32_bf16 v[38:41], v[148:151], v[14:17], v[38:41]
	ds_read_b64_tr_b16 v[168:169], v204 offset:40960
	ds_read_b64_tr_b16 v[170:171], v204 offset:43008
	v_mfma_f32_16x16x32_bf16 v[42:45], v[228:231], v[18:21], 0
	v_mfma_f32_16x16x32_bf16 v[42:45], v[148:151], v[22:25], v[42:45]
	ds_read_b64_tr_b16 v[148:149], v205 offset:40960
	ds_read_b64_tr_b16 v[150:151], v205 offset:43008
	s_waitcnt lgkmcnt(14)
	v_mfma_f32_16x16x32_bf16 v[10:13], v[140:143], v[10:13], 0
	v_mfma_f32_16x16x32_bf16 v[10:13], v[144:147], v[14:17], v[10:13]
	ds_read_b64_tr_b16 v[172:173], v206 offset:40960
	ds_read_b64_tr_b16 v[174:175], v206 offset:43008
	v_mfma_f32_16x16x32_bf16 v[14:17], v[140:143], v[18:21], 0
	v_mfma_f32_16x16x32_bf16 v[14:17], v[144:147], v[22:25], v[14:17]
	ds_read_b64_tr_b16 v[140:141], v203 offset:36864
	ds_read_b64_tr_b16 v[142:143], v203 offset:38912
	v_mfma_f32_16x16x32_bf16 v[18:21], v[6:9], v[26:29], v[66:69]
	v_exp_f32_e32 v116, v116
	s_waitcnt lgkmcnt(14)
	v_mfma_f32_16x16x32_bf16 v[22:25], v[6:9], v[152:155], v[62:65]
	v_mfma_f32_16x16x32_bf16 v[62:65], v[2:5], v[26:29], v[70:73]
	v_exp_f32_e32 v117, v117
	v_mfma_f32_16x16x32_bf16 v[66:69], v[2:5], v[152:155], v[78:81]
	s_nop 0
	ds_read_b64_tr_b16 v[70:71], v204 offset:36864
	ds_read_b64_tr_b16 v[72:73], v204 offset:38912
	v_mfma_f32_16x16x32_bf16 v[74:77], v[6:9], v[156:159], v[74:77]
	v_exp_f32_e32 v118, v118
	v_mfma_f32_16x16x32_bf16 v[78:81], v[2:5], v[156:159], v[82:85]
	v_exp_f32_e32 v119, v119
	s_nop 1
	ds_read_b64_tr_b16 v[82:83], v205 offset:36864
	ds_read_b64_tr_b16 v[84:85], v205 offset:38912
	v_exp_f32_e32 v50, v50
	s_waitcnt lgkmcnt(14)
	v_mfma_f32_16x16x32_bf16 v[86:89], v[6:9], v[136:139], v[86:89]
	s_nop 0
	v_exp_f32_e32 v51, v51
	v_mfma_f32_16x16x32_bf16 v[90:93], v[2:5], v[136:139], v[90:93]
	ds_read_b64_tr_b16 v[136:137], v206 offset:36864
	ds_read_b64_tr_b16 v[138:139], v206 offset:38912
	v_exp_f32_e32 v52, v52
	v_mfma_f32_16x16x32_bf16 v[144:147], v[6:9], v[160:163], v[58:61]
	s_nop 0
	v_exp_f32_e32 v53, v53
	v_mfma_f32_16x16x32_bf16 v[94:97], v[2:5], v[160:163], v[94:97]
	ds_read_b64_tr_b16 v[152:153], v203 offset:45056
	ds_read_b64_tr_b16 v[154:155], v203 offset:47104
	v_exp_f32_e32 v54, v54
	s_waitcnt lgkmcnt(14)
	v_mfma_f32_16x16x32_bf16 v[128:131], v[6:9], v[164:167], v[128:131]
	s_nop 0
	v_exp_f32_e32 v55, v55
	v_mfma_f32_16x16x32_bf16 v[132:135], v[2:5], v[164:167], v[132:135]
	ds_read_b64_tr_b16 v[156:157], v204 offset:45056
	ds_read_b64_tr_b16 v[158:159], v204 offset:47104
	v_exp_f32_e32 v56, v56
	v_mfma_f32_16x16x32_bf16 v[120:123], v[6:9], v[168:171], v[120:123]
	s_nop 0
	v_exp_f32_e32 v57, v57
	v_mfma_f32_16x16x32_bf16 v[124:127], v[2:5], v[168:171], v[124:127]
	ds_read_b64_tr_b16 v[160:161], v205 offset:45056
	ds_read_b64_tr_b16 v[162:163], v205 offset:47104
	v_exp_f32_e32 v46, v46
	s_waitcnt lgkmcnt(14)
	v_mfma_f32_16x16x32_bf16 v[106:109], v[6:9], v[148:151], v[106:109]
	s_nop 0
	v_exp_f32_e32 v47, v47
	v_mfma_f32_16x16x32_bf16 v[110:113], v[2:5], v[148:151], v[110:113]
	ds_read_b64_tr_b16 v[148:149], v206 offset:45056
	ds_read_b64_tr_b16 v[150:151], v206 offset:47104
	v_exp_f32_e32 v48, v48
	v_mfma_f32_16x16x32_bf16 v[98:101], v[6:9], v[172:175], v[98:101]
	s_nop 0
	v_exp_f32_e32 v49, v49
	v_mfma_f32_16x16x32_bf16 v[102:105], v[2:5], v[172:175], v[102:105]
	v_mfma_f32_16x16x32_bf16 v[18:21], v[34:37], v[26:29], v[18:21]
	v_exp_f32_e32 v38, v38
	v_cvt_pk_bf16_f32 v6, v116, v117
	s_waitcnt lgkmcnt(14)
	v_mfma_f32_16x16x32_bf16 v[58:61], v[34:37], v[140:143], v[22:25]
	v_mfma_f32_16x16x32_bf16 v[66:69], v[30:33], v[140:143], v[66:69]
	v_exp_f32_e32 v39, v39
	v_cvt_pk_bf16_f32 v7, v118, v119
	v_mfma_f32_16x16x32_bf16 v[22:25], v[30:33], v[26:29], v[62:65]
	s_waitcnt lgkmcnt(12)
	v_mfma_f32_16x16x32_bf16 v[62:65], v[34:37], v[70:73], v[74:77]
	v_exp_f32_e32 v40, v40
	v_cvt_pk_bf16_f32 v8, v54, v55
	v_mfma_f32_16x16x32_bf16 v[70:73], v[30:33], v[70:73], v[78:81]
	v_exp_f32_e32 v41, v41
	v_cvt_pk_bf16_f32 v9, v56, v57
	s_waitcnt lgkmcnt(10)
	v_mfma_f32_16x16x32_bf16 v[54:57], v[34:37], v[82:85], v[86:89]
	v_exp_f32_e32 v42, v42
	v_cvt_pk_bf16_f32 v2, v50, v51
	v_mfma_f32_16x16x32_bf16 v[74:77], v[30:33], v[82:85], v[90:93]
	v_exp_f32_e32 v43, v43
	v_cvt_pk_bf16_f32 v3, v52, v53
	s_waitcnt lgkmcnt(8)
	v_mfma_f32_16x16x32_bf16 v[50:53], v[34:37], v[136:139], v[144:147]
	v_exp_f32_e32 v44, v44
	v_cvt_pk_bf16_f32 v4, v46, v47
	v_mfma_f32_16x16x32_bf16 v[78:81], v[30:33], v[136:139], v[94:97]
	v_exp_f32_e32 v45, v45
	v_cvt_pk_bf16_f32 v5, v48, v49
	s_waitcnt lgkmcnt(6)
	v_mfma_f32_16x16x32_bf16 v[46:49], v[34:37], v[152:155], v[128:131]
	v_exp_f32_e32 v10, v10
	v_mfma_f32_16x16x32_bf16 v[82:85], v[30:33], v[152:155], v[132:135]
	v_exp_f32_e32 v11, v11
	s_nop 0
	v_exp_f32_e32 v12, v12
	s_waitcnt lgkmcnt(4)
	v_mfma_f32_16x16x32_bf16 v[86:89], v[34:37], v[156:159], v[120:123]
	s_nop 0
	v_exp_f32_e32 v13, v13
	v_mfma_f32_16x16x32_bf16 v[90:93], v[30:33], v[156:159], v[124:127]
	v_exp_f32_e32 v14, v14
	s_waitcnt lgkmcnt(2)
	v_mfma_f32_16x16x32_bf16 v[94:97], v[34:37], v[160:163], v[106:109]
	s_nop 0
	v_exp_f32_e32 v15, v15
	v_mfma_f32_16x16x32_bf16 v[106:109], v[30:33], v[160:163], v[110:113]
	s_waitcnt lgkmcnt(0)
	v_mfma_f32_16x16x32_bf16 v[34:37], v[34:37], v[148:151], v[98:101]
	v_exp_f32_e32 v16, v16
	v_mfma_f32_16x16x32_bf16 v[30:33], v[30:33], v[148:151], v[102:105]
	v_exp_f32_e32 v17, v17
	v_cvt_pk_bf16_f32 v98, v38, v39
	v_cvt_pk_bf16_f32 v99, v40, v41
	v_cvt_pk_bf16_f32 v100, v10, v11
	v_cvt_pk_bf16_f32 v101, v12, v13
	v_cvt_pk_bf16_f32 v102, v42, v43
	v_cvt_pk_bf16_f32 v103, v44, v45
	v_cvt_pk_bf16_f32 v104, v14, v15
	v_cvt_pk_bf16_f32 v105, v16, v17
	s_waitcnt vmcnt(0) lgkmcnt(0)
	s_barrier
; #define MF16(a, b, c) __builtin_amdgcn_mfma_f32_16x16x32_bf16(a, b, c, 0, 0, 0)
; #define MF16(a, b, c) __builtin_amdgcn_mfma_f32_16x16x32_bf16(a, b, c, 0, 0, 0)
; #define VRD16(f) do { vlo[f] = vtr(vpb[(f) & 3] + vo_ + (((f) >> 2) & 1) * 8192 + ((f) >> 3) * 4096); vhi[f] = vtr(vpb[(f) & 3] + vo_ + (((f) >> 2) & 1) * 8192 + ((f) >> 3) * 4096 + 2048); } while (0)
; __device__ __forceinline__ void attn_unit_d16(const UnitDesc& U, char* shm, float lam, const float* subw) {
;     ...
;     { constexpr int vo_ = 3 * VS;
; #pragma unroll
;       for (int f = 0; f < 16; ++f) { VRD16(f);
; #pragma unroll
;           for (int qt = 0; qt < 2; ++qt) o[qt][f & 7] = MF16(__builtin_bit_cast(bf16x8, pa[qt][f >> 3]), VFR16(f), o[qt][f & 7]); }
; #pragma unroll
;       for (int qt = 0; qt < 2; ++qt)
; #pragma unroll
;           for (int ks = 0; ks < 2; ++ks) ls[qt] = MF16(__builtin_bit_cast(bf16x8, pa[qt][ks]), onesb, ls[qt]); }
;     int lane_e = lane; asm volatile("" : "+v"(lane_e));
;     const int c16_e = lane_e & 15, g_e = lane_e >> 4;
;     asm volatile("s_waitcnt lgkmcnt(0)\n\ts_barrier" ::: "memory");
;     float* X = (float*)shm + (wid & 3) * 4096;
;     if (wid >= 4) {
; #pragma unroll
;         for (int qt = 0; qt < 2; ++qt)
; #pragma unroll
;             for (int r = 0; r < 4; ++r) { const float sc = __builtin_amdgcn_rcpf(ls[qt][r]) * lam; const int row = 16 * qt + 4 * g_e + r;
; #pragma unroll
;                 for (int dt = 0; dt < 8; ++dt) X[row * 128 + 16 * dt + c16_e] = o[qt][dt][r] * sc; }
;     }
;     asm volatile("s_waitcnt lgkmcnt(0)\n\ts_barrier" ::: "memory");
;     if (wid < 4) {
; #pragma unroll
;         for (int qt = 0; qt < 2; ++qt)
; #pragma unroll
;             for (int r = 0; r < 4; ++r) { const float sc = __builtin_amdgcn_rcpf(ls[qt][r]); const int row = 16 * qt + 4 * g_e + r;
	ds_read_b64_tr_b16 v[10:11], v203 offset:49152
	ds_read_b64_tr_b16 v[12:13], v203 offset:51200
	ds_read_b64_tr_b16 v[14:15], v203 offset:53248
	ds_read_b64_tr_b16 v[16:17], v203 offset:55296
	v_mov_b32_e32 v1, v193
	s_lshl_b32 s10, s13, 14
	s_waitcnt lgkmcnt(2)
	v_mfma_f32_16x16x32_bf16 v[38:41], v[6:9], v[10:13], v[58:61]
	ds_read_b64_tr_b16 v[42:43], v204 offset:49152
	ds_read_b64_tr_b16 v[44:45], v204 offset:51200
	s_nop 0
	ds_read_b64_tr_b16 v[58:59], v204 offset:53248
	ds_read_b64_tr_b16 v[60:61], v204 offset:55296
	s_and_b32 s10, s10, 0xc000
	s_add_i32 s10, s10, 0
	v_mfma_f32_16x16x32_bf16 v[10:13], v[2:5], v[10:13], v[66:69]
	s_nop 2
	ds_read_b64_tr_b16 v[66:67], v205 offset:49152
	ds_read_b64_tr_b16 v[68:69], v205 offset:51200
	ds_read_b64_tr_b16 v[110:111], v205 offset:53248
	ds_read_b64_tr_b16 v[112:113], v205 offset:55296
	s_cmpk_gt_u32 s12, 0xff
	s_waitcnt lgkmcnt(6)
	v_mfma_f32_16x16x32_bf16 v[62:65], v[6:9], v[42:45], v[62:65]
	v_mfma_f32_16x16x32_bf16 v[42:45], v[2:5], v[42:45], v[70:73]
	s_nop 2
	ds_read_b64_tr_b16 v[70:71], v206 offset:49152
	ds_read_b64_tr_b16 v[72:73], v206 offset:51200
	ds_read_b64_tr_b16 v[116:117], v206 offset:53248
	ds_read_b64_tr_b16 v[118:119], v206 offset:55296
	s_waitcnt lgkmcnt(2)
	v_mfma_f32_16x16x32_bf16 v[50:53], v[6:9], v[70:73], v[50:53]
	v_mfma_f32_16x16x32_bf16 v[78:81], v[2:5], v[70:73], v[78:81]
	ds_read_b64_tr_b16 v[70:71], v203 offset:57344
	ds_read_b64_tr_b16 v[72:73], v203 offset:59392
	ds_read_b64_tr_b16 v[120:121], v203 offset:61440
	ds_read_b64_tr_b16 v[122:123], v203 offset:63488
	s_waitcnt lgkmcnt(2)
	v_mfma_f32_16x16x32_bf16 v[46:49], v[6:9], v[70:73], v[46:49]
	v_mfma_f32_16x16x32_bf16 v[82:85], v[2:5], v[70:73], v[82:85]
	ds_read_b64_tr_b16 v[70:71], v204 offset:57344
	ds_read_b64_tr_b16 v[72:73], v204 offset:59392
	ds_read_b64_tr_b16 v[124:125], v204 offset:61440
	ds_read_b64_tr_b16 v[126:127], v204 offset:63488
	s_waitcnt lgkmcnt(2)
	v_mfma_f32_16x16x32_bf16 v[86:89], v[6:9], v[70:73], v[86:89]
	v_mfma_f32_16x16x32_bf16 v[90:93], v[2:5], v[70:73], v[90:93]
	ds_read_b64_tr_b16 v[70:71], v205 offset:57344
	ds_read_b64_tr_b16 v[72:73], v205 offset:59392
	ds_read_b64_tr_b16 v[128:129], v205 offset:61440
	ds_read_b64_tr_b16 v[130:131], v205 offset:63488
	s_waitcnt lgkmcnt(2)
	v_mfma_f32_16x16x32_bf16 v[94:97], v[6:9], v[70:73], v[94:97]
	v_mfma_f32_16x16x32_bf16 v[106:109], v[2:5], v[70:73], v[106:109]
	ds_read_b64_tr_b16 v[70:71], v206 offset:57344
	ds_read_b64_tr_b16 v[72:73], v206 offset:59392
	ds_read_b64_tr_b16 v[132:133], v206 offset:61440
	ds_read_b64_tr_b16 v[134:135], v206 offset:63488
	s_waitcnt lgkmcnt(0)
	s_barrier
	v_mfma_f32_16x16x32_bf16 v[54:57], v[6:9], v[66:69], v[54:57]
	v_mfma_f32_16x16x32_bf16 v[66:69], v[2:5], v[66:69], v[74:77]
	s_waitcnt lgkmcnt(2)
	v_mfma_f32_16x16x32_bf16 v[136:139], v[6:9], v[70:73], v[34:37]
	v_mfma_f32_16x16x32_bf16 v[140:143], v[2:5], v[70:73], v[30:33]
	v_mfma_f32_16x16x32_bf16 v[6:9], v[6:9], v[26:29], v[18:21]
	v_mfma_f32_16x16x32_bf16 v[2:5], v[2:5], v[26:29], v[22:25]
	v_mfma_f32_16x16x32_bf16 v[74:77], v[98:101], v[58:61], v[62:65]
	v_mfma_f32_16x16x32_bf16 v[42:45], v[102:105], v[58:61], v[42:45]
	v_mfma_f32_16x16x32_bf16 v[58:61], v[98:101], v[110:113], v[54:57]
	v_mfma_f32_16x16x32_bf16 v[54:57], v[98:101], v[124:127], v[86:89]
	v_mfma_f32_16x16x32_bf16 v[86:89], v[98:101], v[26:29], v[6:9]
	v_mfma_f32_16x16x32_bf16 v[2:5], v[102:105], v[26:29], v[2:5]
	v_mfma_f32_16x16x32_bf16 v[70:73], v[98:101], v[14:17], v[38:41]
	s_nop 5
	v_rcp_f32_e32 v21, v86
	v_rcp_f32_e32 v20, v87
	v_rcp_f32_e32 v19, v88
	v_mfma_f32_16x16x32_bf16 v[38:41], v[102:105], v[14:17], v[10:13]
	v_rcp_f32_e32 v18, v89
	v_rcp_f32_e32 v9, v2
	v_rcp_f32_e32 v8, v3
	v_mfma_f32_16x16x32_bf16 v[10:13], v[102:105], v[120:123], v[82:85]
	s_nop 2
	v_and_b32_e32 v84, 15, v1
	v_ashrrev_i32_e32 v82, 4, v1
	v_lshlrev_b32_e32 v1, 11, v82
	v_lshlrev_b32_e32 v6, 2, v84
	v_mfma_f32_16x16x32_bf16 v[30:33], v[102:105], v[110:113], v[66:69]
	v_add3_u32 v7, s10, v6, v1
	v_rcp_f32_e32 v6, v4
	v_rcp_f32_e32 v1, v5
	v_mfma_f32_16x16x32_bf16 v[62:65], v[98:101], v[116:119], v[50:53]
	v_mfma_f32_16x16x32_bf16 v[34:37], v[102:105], v[116:119], v[78:81]
	v_mfma_f32_16x16x32_bf16 v[66:69], v[98:101], v[120:123], v[46:49]
	v_mfma_f32_16x16x32_bf16 v[14:17], v[102:105], v[124:127], v[90:93]
	v_mfma_f32_16x16x32_bf16 v[50:53], v[98:101], v[128:131], v[94:97]
	v_mfma_f32_16x16x32_bf16 v[46:49], v[102:105], v[128:131], v[106:109]
	s_waitcnt lgkmcnt(0)
	v_mfma_f32_16x16x32_bf16 v[78:81], v[98:101], v[132:135], v[136:139]
	v_mfma_f32_16x16x32_bf16 v[2:5], v[102:105], v[132:135], v[140:143]
	s_cbranch_scc0 .LBB0_447
; __device__ __forceinline__ void attn_unit_d16(const UnitDesc& U, char* shm, float lam, const float* subw) {
;     ...
;     if (wid >= 4) {
; #pragma unroll
;         for (int qt = 0; qt < 2; ++qt)
; #pragma unroll
;             for (int r = 0; r < 4; ++r) { const float sc = __builtin_amdgcn_rcpf(ls[qt][r]) * lam; const int row = 16 * qt + 4 * g_e + r;
; #pragma unroll
;                 for (int dt = 0; dt < 8; ++dt) X[row * 128 + 16 * dt + c16_e] = o[qt][dt][r] * sc; }
;     }
	v_mul_f32_e32 v22, v181, v21
	v_mul_f32_e32 v23, v70, v22
	v_mul_f32_e32 v24, v74, v22
	ds_write2_b32 v7, v23, v24 offset1:16
	v_mul_f32_e32 v23, v58, v22
	v_mul_f32_e32 v24, v62, v22
	ds_write2_b32 v7, v23, v24 offset0:32 offset1:48
	v_mul_f32_e32 v23, v66, v22
	v_mul_f32_e32 v24, v54, v22
	ds_write2_b32 v7, v23, v24 offset0:64 offset1:80
	v_mul_f32_e32 v23, v50, v22
	v_mul_f32_e32 v22, v78, v22
	ds_write2_b32 v7, v23, v22 offset0:96 offset1:112
	v_mul_f32_e32 v22, v181, v20
	v_mul_f32_e32 v23, v71, v22
	v_mul_f32_e32 v24, v75, v22
	ds_write2_b32 v7, v23, v24 offset0:128 offset1:144
	v_mul_f32_e32 v23, v59, v22
	v_mul_f32_e32 v24, v63, v22
	ds_write2_b32 v7, v23, v24 offset0:160 offset1:176
	v_mul_f32_e32 v23, v67, v22
	v_mul_f32_e32 v24, v55, v22
	ds_write2_b32 v7, v23, v24 offset0:192 offset1:208
	v_mul_f32_e32 v23, v51, v22
	v_mul_f32_e32 v22, v79, v22
	ds_write2_b32 v7, v23, v22 offset0:224 offset1:240
	v_mul_f32_e32 v22, v181, v19
	v_mul_f32_e32 v23, v72, v22
	v_mul_f32_e32 v24, v76, v22
	v_add_u32_e32 v25, 0x400, v7
	ds_write2_b32 v25, v23, v24 offset1:16
	v_mul_f32_e32 v23, v60, v22
	v_mul_f32_e32 v24, v64, v22
	ds_write2_b32 v25, v23, v24 offset0:32 offset1:48
	v_mul_f32_e32 v23, v68, v22
	v_mul_f32_e32 v24, v56, v22
	ds_write2_b32 v25, v23, v24 offset0:64 offset1:80
	v_mul_f32_e32 v23, v52, v22
	v_mul_f32_e32 v22, v80, v22
	ds_write2_b32 v25, v23, v22 offset0:96 offset1:112
	v_mul_f32_e32 v22, v181, v18
	v_mul_f32_e32 v23, v73, v22
	v_mul_f32_e32 v24, v77, v22
	ds_write2_b32 v25, v23, v24 offset0:128 offset1:144
	v_mul_f32_e32 v23, v61, v22
	v_mul_f32_e32 v24, v65, v22
	ds_write2_b32 v25, v23, v24 offset0:160 offset1:176
	v_mul_f32_e32 v23, v69, v22
	v_mul_f32_e32 v24, v57, v22
	ds_write2_b32 v25, v23, v24 offset0:192 offset1:208
	v_mul_f32_e32 v23, v53, v22
	v_mul_f32_e32 v22, v81, v22
	ds_write2_b32 v25, v23, v22 offset0:224 offset1:240
	v_mul_f32_e32 v22, v181, v9
	v_mul_f32_e32 v23, v38, v22
	v_mul_f32_e32 v24, v42, v22
	v_add_u32_e32 v25, 0x2000, v7
	ds_write2_b32 v25, v23, v24 offset1:16
	v_mul_f32_e32 v23, v30, v22
	v_mul_f32_e32 v24, v34, v22
	ds_write2_b32 v25, v23, v24 offset0:32 offset1:48
	v_mul_f32_e32 v23, v10, v22
	v_mul_f32_e32 v24, v14, v22
	ds_write2_b32 v25, v23, v24 offset0:64 offset1:80
	v_mul_f32_e32 v23, v46, v22
	v_mul_f32_e32 v22, v2, v22
	ds_write2_b32 v25, v23, v22 offset0:96 offset1:112
	v_mul_f32_e32 v22, v181, v8
	v_mul_f32_e32 v23, v39, v22
	v_mul_f32_e32 v24, v43, v22
	ds_write2_b32 v25, v23, v24 offset0:128 offset1:144
	v_mul_f32_e32 v23, v31, v22
	v_mul_f32_e32 v24, v35, v22
	ds_write2_b32 v25, v23, v24 offset0:160 offset1:176
	v_mul_f32_e32 v23, v11, v22
	v_mul_f32_e32 v24, v15, v22
	ds_write2_b32 v25, v23, v24 offset0:192 offset1:208
	v_mul_f32_e32 v23, v47, v22
	v_mul_f32_e32 v22, v3, v22
	ds_write2_b32 v25, v23, v22 offset0:224 offset1:240
	v_mul_f32_e32 v22, v181, v6
	v_mul_f32_e32 v23, v40, v22
	v_mul_f32_e32 v24, v44, v22
	v_add_u32_e32 v25, 0x2400, v7
	ds_write2_b32 v25, v23, v24 offset1:16
	v_mul_f32_e32 v23, v32, v22
	v_mul_f32_e32 v24, v36, v22
	ds_write2_b32 v25, v23, v24 offset0:32 offset1:48
	v_mul_f32_e32 v23, v12, v22
	v_mul_f32_e32 v24, v16, v22
	ds_write2_b32 v25, v23, v24 offset0:64 offset1:80
	v_mul_f32_e32 v23, v48, v22
	v_mul_f32_e32 v22, v4, v22
	ds_write2_b32 v25, v23, v22 offset0:96 offset1:112
	v_mul_f32_e32 v22, v181, v1
	v_mul_f32_e32 v23, v41, v22
	v_mul_f32_e32 v24, v45, v22
	ds_write2_b32 v25, v23, v24 offset0:128 offset1:144
	v_mul_f32_e32 v23, v33, v22
	v_mul_f32_e32 v24, v37, v22
	ds_write2_b32 v25, v23, v24 offset0:160 offset1:176
	v_mul_f32_e32 v23, v13, v22
	v_mul_f32_e32 v24, v17, v22
	ds_write2_b32 v25, v23, v24 offset0:192 offset1:208
	v_mul_f32_e32 v23, v49, v22
	v_mul_f32_e32 v22, v5, v22
	ds_write2_b32 v25, v23, v22 offset0:224 offset1:240
